# baseline (speedup 1.0000x reference)
; #define PG8_STAGE(bufoff, gbase, voff) do { _Pragma("unroll") for (int _i = 0; _i < 2; ++_i) \
;         __builtin_amdgcn_global_load_lds((const unsigned*)((const char*)(gbase) + (voff)[_i]), (PG8_LAS unsigned*)(lds + (bufoff) + ldsw + _i * 8192), 16, 0, 0); } while (0)
; #define PG8_LDA(dst, b, h) do { _Pragma("unroll") for (int m = 0; m < 4; ++m) _Pragma("unroll") for (int k = 0; k < 2; ++k) dst[m][k] = *(const PG8_LAS bf16x8*)(lds + PG8_SA(b, h) + aoff + m * 2048 + k * 1024); } while (0)
; #define PG8_LDB(dst, b, h) do { _Pragma("unroll") for (int n = 0; n < 2; ++n) _Pragma("unroll") for (int k = 0; k < 2; ++k) dst[n][k] = *(const PG8_LAS bf16x8*)(lds + PG8_SB(b, h) + boff + n * 2048 + k * 1024); } while (0)
; #define PG8_MMA(ai, bj, At, Bt) do { __builtin_amdgcn_s_setprio(1); _Pragma("unroll") for (int m = 0; m < 4; ++m) _Pragma("unroll") for (int n = 0; n < 2; ++n) _Pragma("unroll") for (int k = 0; k < 2; ++k) \
;         acc[ai][bj][m][n] = __builtin_amdgcn_mfma_f32_16x16x32_bf16(Bt[n][k], At[m][k], acc[ai][bj][m][n], 0, 0, 0); __builtin_amdgcn_s_setprio(0); } while (0)
; #define PG8_WAIT_V(n) asm volatile("s_waitcnt vmcnt(" #n ")" ::: "memory")
; #define PG8_WAIT_L(n) asm volatile("s_waitcnt lgkmcnt(" #n ")" ::: "memory")
; #define PG8_BAR __builtin_amdgcn_s_barrier()
; #define PG8_SCHED __builtin_amdgcn_sched_barrier(0)
; template <class Epi, class Sched, bool ALIGN_EPI = false, bool SP2 = false>
; __device__ __forceinline__ void gemm_phase(PG8_LAS unsigned char* lds, const Gemm g, const Sched& S, const Epi& E) {
;     ...
;             PG8_LDB(B0, 0, 0); PG8_LDB(B1, 0, 1); PG8_SCHED; PG8_LDA(At, 0, 0); PG8_STAGE(PG8_SA(1, 1), a1 + hstep, voffA);
;             PG8_WAIT_V(8); PG8_WAIT_L(0); PG8_BAR; PG8_MMA(0, 0, At, B0); PG8_MMA(0, 1, At, B1); PG8_BAR; PG8_SCHED;
;             PG8_LDA(At, 0, 1); PG8_STAGE(PG8_SB(0, 0), b2, voffB); PG8_STAGE(PG8_SB(0, 1), b2 + hstep, voffB); PG8_STAGE(PG8_SA(0, 0), a2, voffA);
;             PG8_WAIT_V(8); PG8_WAIT_L(0); PG8_BAR; PG8_MMA(1, 0, At, B0); PG8_MMA(1, 1, At, B1); PG8_BAR; PG8_SCHED;
.LBB0_299:
	s_add_u32 s42, s86, 0x100
	s_addc_u32 s43, s87, 0
	s_add_i32 s9, 0, 0x10000
	s_cmp_eq_u32 s70, 40
	s_cselect_b32 s89, s7, s43
	s_cselect_b32 s88, s6, s42
	s_cselect_b32 s55, s85, s69
	s_cselect_b32 s54, s84, s68
	s_add_i32 s71, 0, 0x14000
	v_add_u32_e32 v136, s9, v213
	v_add_u32_e32 v160, s71, v213
	ds_read_b128 v[124:127], v136
	ds_read_b128 v[128:131], v136 offset:1024
	ds_read_b128 v[132:135], v136 offset:2048
	ds_read_b128 v[136:139], v136 offset:3072
	ds_read_b128 v[148:151], v160
	ds_read_b128 v[152:155], v160 offset:1024
	ds_read_b128 v[156:159], v160 offset:2048
	ds_read_b128 v[160:163], v160 offset:3072
	v_lshl_add_u64 v[196:197], s[86:87], 0, v[222:223]
	s_add_i32 m0, s3, 0xc000
	ds_read_b128 v[164:167], v251
	ds_read_b128 v[168:171], v251 offset:1024
	ds_read_b128 v[172:175], v251 offset:2048
	ds_read_b128 v[176:179], v251 offset:3072
	ds_read_b128 v[180:183], v251 offset:4096
	ds_read_b128 v[184:187], v251 offset:5120
	ds_read_b128 v[188:191], v251 offset:6144
	ds_read_b128 v[192:195], v251 offset:7168
	global_load_lds_dwordx4 v[196:197], off
	v_lshl_add_u64 v[196:197], s[86:87], 0, v[220:221]
	s_add_i32 m0, s3, 0xe000
	s_nop 0
	global_load_lds_dwordx4 v[196:197], off
	s_waitcnt vmcnt(8)
	s_waitcnt lgkmcnt(0)
	s_barrier
	s_setprio 1
	s_waitcnt lgkmcnt(0)
	v_mfma_f32_16x16x32_bf16 v[144:147], v[124:127], v[164:167], v[144:147]
	v_mfma_f32_16x16x32_bf16 v[140:143], v[132:135], v[164:167], v[140:143]
	v_mfma_f32_16x16x32_bf16 v[112:115], v[124:127], v[172:175], v[112:115]
	v_mfma_f32_16x16x32_bf16 v[108:111], v[132:135], v[172:175], v[108:111]
	v_mfma_f32_16x16x32_bf16 v[96:99], v[124:127], v[180:183], v[96:99]
	v_mfma_f32_16x16x32_bf16 v[92:95], v[132:135], v[180:183], v[92:95]
	v_mfma_f32_16x16x32_bf16 v[80:83], v[124:127], v[188:191], v[80:83]
	v_mfma_f32_16x16x32_bf16 v[76:79], v[132:135], v[188:191], v[76:79]
	v_mfma_f32_16x16x32_bf16 v[144:147], v[128:131], v[168:171], v[144:147]
	v_mfma_f32_16x16x32_bf16 v[140:143], v[136:139], v[168:171], v[140:143]
	v_mfma_f32_16x16x32_bf16 v[112:115], v[128:131], v[176:179], v[112:115]
	v_mfma_f32_16x16x32_bf16 v[108:111], v[136:139], v[176:179], v[108:111]
	v_mfma_f32_16x16x32_bf16 v[96:99], v[128:131], v[184:187], v[96:99]
	v_mfma_f32_16x16x32_bf16 v[92:95], v[136:139], v[184:187], v[92:95]
	v_mfma_f32_16x16x32_bf16 v[80:83], v[128:131], v[192:195], v[80:83]
	v_mfma_f32_16x16x32_bf16 v[76:79], v[136:139], v[192:195], v[76:79]
	s_setprio 0
	s_setprio 1
	v_mfma_f32_16x16x32_bf16 v[120:123], v[148:151], v[164:167], v[120:123]
	v_mfma_f32_16x16x32_bf16 v[116:119], v[156:159], v[164:167], v[116:119]
	v_mfma_f32_16x16x32_bf16 v[104:107], v[148:151], v[172:175], v[104:107]
	v_mfma_f32_16x16x32_bf16 v[100:103], v[156:159], v[172:175], v[100:103]
	v_mfma_f32_16x16x32_bf16 v[88:91], v[148:151], v[180:183], v[88:91]
	v_mfma_f32_16x16x32_bf16 v[84:87], v[156:159], v[180:183], v[84:87]
	v_mfma_f32_16x16x32_bf16 v[72:75], v[148:151], v[188:191], v[72:75]
	v_mfma_f32_16x16x32_bf16 v[68:71], v[156:159], v[188:191], v[68:71]
	v_mfma_f32_16x16x32_bf16 v[120:123], v[152:155], v[168:171], v[120:123]
	v_mfma_f32_16x16x32_bf16 v[116:119], v[160:163], v[168:171], v[116:119]
	v_mfma_f32_16x16x32_bf16 v[104:107], v[152:155], v[176:179], v[104:107]
	v_mfma_f32_16x16x32_bf16 v[100:103], v[160:163], v[176:179], v[100:103]
	v_mfma_f32_16x16x32_bf16 v[88:91], v[152:155], v[184:187], v[88:91]
	v_mfma_f32_16x16x32_bf16 v[84:87], v[160:163], v[184:187], v[84:87]
	v_mfma_f32_16x16x32_bf16 v[72:75], v[152:155], v[192:195], v[72:75]
	v_mfma_f32_16x16x32_bf16 v[68:71], v[160:163], v[192:195], v[68:71]
	s_setprio 0
	s_barrier
	s_add_i32 s9, s9, s1
	v_lshl_add_u64 v[196:197], s[54:55], 0, v[214:215]
	s_mov_b32 m0, s9
	ds_read_b128 v[164:167], v251 offset:16384
	ds_read_b128 v[168:171], v251 offset:17408
	ds_read_b128 v[172:175], v251 offset:18432
	ds_read_b128 v[176:179], v251 offset:19456
	ds_read_b128 v[180:183], v251 offset:20480
	ds_read_b128 v[184:187], v251 offset:21504
	ds_read_b128 v[188:191], v251 offset:22528
	ds_read_b128 v[192:195], v251 offset:23552
	global_load_lds_dwordx4 v[196:197], off
	s_add_i32 m0, s9, 0x2000
	s_add_u32 s58, s54, 0xb0000
	v_lshl_add_u64 v[198:199], s[54:55], 0, v[218:219]
	s_addc_u32 s59, s55, 0
	s_add_i32 s9, s71, s1
	global_load_lds_dwordx4 v[198:199], off
	v_lshl_add_u64 v[200:201], s[58:59], 0, v[214:215]
	s_mov_b32 m0, s9
	v_lshl_add_u64 v[202:203], s[88:89], 0, v[216:217]
	global_load_lds_dwordx4 v[200:201], off
	v_lshl_add_u64 v[200:201], s[58:59], 0, v[218:219]
	s_add_i32 m0, s9, 0x2000
	s_nop 0
	global_load_lds_dwordx4 v[200:201], off
	v_lshl_add_u64 v[200:201], s[88:89], 0, v[0:1]
	s_mov_b32 m0, s3
	s_nop 0
	global_load_lds_dwordx4 v[200:201], off
	s_mov_b32 m0, s8
	s_nop 0
	global_load_lds_dwordx4 v[202:203], off
	s_waitcnt vmcnt(8)
	s_waitcnt lgkmcnt(0)
	s_barrier
; #define PG8_STAGE(bufoff, gbase, voff) do { _Pragma("unroll") for (int _i = 0; _i < 2; ++_i) \
;         __builtin_amdgcn_global_load_lds((const unsigned*)((const char*)(gbase) + (voff)[_i]), (PG8_LAS unsigned*)(lds + (bufoff) + ldsw + _i * 8192), 16, 0, 0); } while (0)
; #define PG8_LDA(dst, b, h) do { _Pragma("unroll") for (int m = 0; m < 4; ++m) _Pragma("unroll") for (int k = 0; k < 2; ++k) dst[m][k] = *(const PG8_LAS bf16x8*)(lds + PG8_SA(b, h) + aoff + m * 2048 + k * 1024); } while (0)
; #define PG8_LDB(dst, b, h) do { _Pragma("unroll") for (int n = 0; n < 2; ++n) _Pragma("unroll") for (int k = 0; k < 2; ++k) dst[n][k] = *(const PG8_LAS bf16x8*)(lds + PG8_SB(b, h) + boff + n * 2048 + k * 1024); } while (0)
; #define PG8_MMA(ai, bj, At, Bt) do { __builtin_amdgcn_s_setprio(1); _Pragma("unroll") for (int m = 0; m < 4; ++m) _Pragma("unroll") for (int n = 0; n < 2; ++n) _Pragma("unroll") for (int k = 0; k < 2; ++k) \
;         acc[ai][bj][m][n] = __builtin_amdgcn_mfma_f32_16x16x32_bf16(Bt[n][k], At[m][k], acc[ai][bj][m][n], 0, 0, 0); __builtin_amdgcn_s_setprio(0); } while (0)
; #define PG8_WAIT_V(n) asm volatile("s_waitcnt vmcnt(" #n ")" ::: "memory")
; #define PG8_WAIT_L(n) asm volatile("s_waitcnt lgkmcnt(" #n ")" ::: "memory")
; #define PG8_BAR __builtin_amdgcn_s_barrier()
; #define PG8_SCHED __builtin_amdgcn_sched_barrier(0)
; template <class Epi, class Sched, bool ALIGN_EPI = false, bool SP2 = false>
; __device__ __forceinline__ void gemm_phase(PG8_LAS unsigned char* lds, const Gemm g, const Sched& S, const Epi& E) {
;     ...
;             PG8_WAIT_V(8); PG8_WAIT_L(0); PG8_BAR; PG8_MMA(1, 0, At, B0); PG8_MMA(1, 1, At, B1); PG8_BAR; PG8_SCHED;
;             PG8_LDB(B0, 1, 0); PG8_LDB(B1, 1, 1); PG8_SCHED; PG8_LDA(At, 1, 0); PG8_STAGE(PG8_SA(0, 1), a2 + hstep, voffA);
;             PG8_WAIT_V(8); PG8_WAIT_L(0); PG8_BAR; PG8_MMA(0, 0, At, B0); PG8_MMA(0, 1, At, B1); PG8_BAR; PG8_SCHED;
	s_setprio 1
	s_waitcnt lgkmcnt(0)
	v_mfma_f32_16x16x32_bf16 v[64:67], v[124:127], v[164:167], v[64:67]
	v_mfma_f32_16x16x32_bf16 v[60:63], v[132:135], v[164:167], v[60:63]
	v_mfma_f32_16x16x32_bf16 v[48:51], v[124:127], v[172:175], v[48:51]
	v_mfma_f32_16x16x32_bf16 v[44:47], v[132:135], v[172:175], v[44:47]
	v_mfma_f32_16x16x32_bf16 v[32:35], v[124:127], v[180:183], v[32:35]
	v_mfma_f32_16x16x32_bf16 v[28:31], v[132:135], v[180:183], v[28:31]
	v_mfma_f32_16x16x32_bf16 v[16:19], v[124:127], v[188:191], v[16:19]
	v_mfma_f32_16x16x32_bf16 v[12:15], v[132:135], v[188:191], v[12:15]
	v_mfma_f32_16x16x32_bf16 v[64:67], v[128:131], v[168:171], v[64:67]
	v_mfma_f32_16x16x32_bf16 v[60:63], v[136:139], v[168:171], v[60:63]
	v_mfma_f32_16x16x32_bf16 v[48:51], v[128:131], v[176:179], v[48:51]
	v_mfma_f32_16x16x32_bf16 v[44:47], v[136:139], v[176:179], v[44:47]
	v_mfma_f32_16x16x32_bf16 v[32:35], v[128:131], v[184:187], v[32:35]
	v_mfma_f32_16x16x32_bf16 v[28:31], v[136:139], v[184:187], v[28:31]
	v_mfma_f32_16x16x32_bf16 v[16:19], v[128:131], v[192:195], v[16:19]
	v_mfma_f32_16x16x32_bf16 v[12:15], v[136:139], v[192:195], v[12:15]
	s_setprio 0
	s_setprio 1
	v_mfma_f32_16x16x32_bf16 v[56:59], v[148:151], v[164:167], v[56:59]
	v_mfma_f32_16x16x32_bf16 v[52:55], v[156:159], v[164:167], v[52:55]
	v_mfma_f32_16x16x32_bf16 v[40:43], v[148:151], v[172:175], v[40:43]
	v_mfma_f32_16x16x32_bf16 v[36:39], v[156:159], v[172:175], v[36:39]
	v_mfma_f32_16x16x32_bf16 v[24:27], v[148:151], v[180:183], v[24:27]
	v_mfma_f32_16x16x32_bf16 v[20:23], v[156:159], v[180:183], v[20:23]
	v_mfma_f32_16x16x32_bf16 v[8:11], v[148:151], v[188:191], v[8:11]
	v_mfma_f32_16x16x32_bf16 v[4:7], v[156:159], v[188:191], v[4:7]
	v_mfma_f32_16x16x32_bf16 v[56:59], v[152:155], v[168:171], v[56:59]
	v_mfma_f32_16x16x32_bf16 v[52:55], v[160:163], v[168:171], v[52:55]
	v_mfma_f32_16x16x32_bf16 v[40:43], v[152:155], v[176:179], v[40:43]
	v_mfma_f32_16x16x32_bf16 v[36:39], v[160:163], v[176:179], v[36:39]
	v_mfma_f32_16x16x32_bf16 v[24:27], v[152:155], v[184:187], v[24:27]
	v_mfma_f32_16x16x32_bf16 v[20:23], v[160:163], v[184:187], v[20:23]
	v_mfma_f32_16x16x32_bf16 v[8:11], v[152:155], v[192:195], v[8:11]
	v_mfma_f32_16x16x32_bf16 v[4:7], v[160:163], v[192:195], v[4:7]
	s_setprio 0
	s_barrier
	s_add_i32 s9, 0, 0x18000
	s_add_i32 s71, 0, 0x1c000
	v_add_u32_e32 v136, s9, v213
	v_add_u32_e32 v160, s71, v213
	ds_read_b128 v[124:127], v136
	ds_read_b128 v[128:131], v136 offset:1024
	ds_read_b128 v[132:135], v136 offset:2048
	ds_read_b128 v[136:139], v136 offset:3072
	ds_read_b128 v[148:151], v160
	ds_read_b128 v[152:155], v160 offset:1024
	ds_read_b128 v[156:159], v160 offset:2048
	ds_read_b128 v[160:163], v160 offset:3072
	s_add_u32 s58, s88, 0xb0000
	s_addc_u32 s59, s89, 0
	s_mov_b32 m0, s38
	v_lshl_add_u64 v[204:205], s[58:59], 0, v[0:1]
	ds_read_b128 v[164:167], v251 offset:32768
	ds_read_b128 v[168:171], v251 offset:33792
	ds_read_b128 v[172:175], v251 offset:34816
	ds_read_b128 v[176:179], v251 offset:35840
	ds_read_b128 v[180:183], v251 offset:36864
	ds_read_b128 v[184:187], v251 offset:37888
	ds_read_b128 v[188:191], v251 offset:38912
	ds_read_b128 v[192:195], v251 offset:39936
	global_load_lds_dwordx4 v[204:205], off
	v_lshl_add_u64 v[204:205], s[58:59], 0, v[216:217]
	s_mov_b32 m0, s45
	s_nop 0
	global_load_lds_dwordx4 v[204:205], off
	s_waitcnt vmcnt(8)
	s_waitcnt lgkmcnt(0)
	s_barrier
	s_setprio 1
	s_waitcnt lgkmcnt(0)
	v_mfma_f32_16x16x32_bf16 v[144:147], v[124:127], v[164:167], v[144:147]
	v_mfma_f32_16x16x32_bf16 v[140:143], v[132:135], v[164:167], v[140:143]
	v_mfma_f32_16x16x32_bf16 v[112:115], v[124:127], v[172:175], v[112:115]
	v_mfma_f32_16x16x32_bf16 v[108:111], v[132:135], v[172:175], v[108:111]
	v_mfma_f32_16x16x32_bf16 v[96:99], v[124:127], v[180:183], v[96:99]
	v_mfma_f32_16x16x32_bf16 v[92:95], v[132:135], v[180:183], v[92:95]
	v_mfma_f32_16x16x32_bf16 v[80:83], v[124:127], v[188:191], v[80:83]
	v_mfma_f32_16x16x32_bf16 v[76:79], v[132:135], v[188:191], v[76:79]
	v_mfma_f32_16x16x32_bf16 v[144:147], v[128:131], v[168:171], v[144:147]
	v_mfma_f32_16x16x32_bf16 v[140:143], v[136:139], v[168:171], v[140:143]
	v_mfma_f32_16x16x32_bf16 v[112:115], v[128:131], v[176:179], v[112:115]
	v_mfma_f32_16x16x32_bf16 v[108:111], v[136:139], v[176:179], v[108:111]
	v_mfma_f32_16x16x32_bf16 v[96:99], v[128:131], v[184:187], v[96:99]
	v_mfma_f32_16x16x32_bf16 v[92:95], v[136:139], v[184:187], v[92:95]
	v_mfma_f32_16x16x32_bf16 v[80:83], v[128:131], v[192:195], v[80:83]
	v_mfma_f32_16x16x32_bf16 v[76:79], v[136:139], v[192:195], v[76:79]
	s_setprio 0
	s_setprio 1
	v_mfma_f32_16x16x32_bf16 v[120:123], v[148:151], v[164:167], v[120:123]
	v_mfma_f32_16x16x32_bf16 v[116:119], v[156:159], v[164:167], v[116:119]
	v_mfma_f32_16x16x32_bf16 v[104:107], v[148:151], v[172:175], v[104:107]
	v_mfma_f32_16x16x32_bf16 v[100:103], v[156:159], v[172:175], v[100:103]
	v_mfma_f32_16x16x32_bf16 v[88:91], v[148:151], v[180:183], v[88:91]
	v_mfma_f32_16x16x32_bf16 v[84:87], v[156:159], v[180:183], v[84:87]
	v_mfma_f32_16x16x32_bf16 v[72:75], v[148:151], v[188:191], v[72:75]
	v_mfma_f32_16x16x32_bf16 v[68:71], v[156:159], v[188:191], v[68:71]
	v_mfma_f32_16x16x32_bf16 v[120:123], v[152:155], v[168:171], v[120:123]
	v_mfma_f32_16x16x32_bf16 v[116:119], v[160:163], v[168:171], v[116:119]
	v_mfma_f32_16x16x32_bf16 v[104:107], v[152:155], v[176:179], v[104:107]
	v_mfma_f32_16x16x32_bf16 v[100:103], v[160:163], v[176:179], v[100:103]
	v_mfma_f32_16x16x32_bf16 v[88:91], v[152:155], v[184:187], v[88:91]
	v_mfma_f32_16x16x32_bf16 v[84:87], v[160:163], v[184:187], v[84:87]
	v_mfma_f32_16x16x32_bf16 v[72:75], v[152:155], v[192:195], v[72:75]
	v_mfma_f32_16x16x32_bf16 v[68:71], v[160:163], v[192:195], v[68:71]
	s_setprio 0
	s_barrier
; #define PG8_STAGE(bufoff, gbase, voff) do { _Pragma("unroll") for (int _i = 0; _i < 2; ++_i) \
;         __builtin_amdgcn_global_load_lds((const unsigned*)((const char*)(gbase) + (voff)[_i]), (PG8_LAS unsigned*)(lds + (bufoff) + ldsw + _i * 8192), 16, 0, 0); } while (0)
; #define PG8_LDA(dst, b, h) do { _Pragma("unroll") for (int m = 0; m < 4; ++m) _Pragma("unroll") for (int k = 0; k < 2; ++k) dst[m][k] = *(const PG8_LAS bf16x8*)(lds + PG8_SA(b, h) + aoff + m * 2048 + k * 1024); } while (0)
; #define PG8_MMA(ai, bj, At, Bt) do { __builtin_amdgcn_s_setprio(1); _Pragma("unroll") for (int m = 0; m < 4; ++m) _Pragma("unroll") for (int n = 0; n < 2; ++n) _Pragma("unroll") for (int k = 0; k < 2; ++k) \
;         acc[ai][bj][m][n] = __builtin_amdgcn_mfma_f32_16x16x32_bf16(Bt[n][k], At[m][k], acc[ai][bj][m][n], 0, 0, 0); __builtin_amdgcn_s_setprio(0); } while (0)
; #define PG8_WAIT_V(n) asm volatile("s_waitcnt vmcnt(" #n ")" ::: "memory")
; #define PG8_WAIT_L(n) asm volatile("s_waitcnt lgkmcnt(" #n ")" ::: "memory")
; #define PG8_BAR __builtin_amdgcn_s_barrier()
; #define PG8_SCHED __builtin_amdgcn_sched_barrier(0)
; template <class Epi, class Sched, bool ALIGN_EPI = false, bool SP2 = false>
; __device__ __forceinline__ void gemm_phase(PG8_LAS unsigned char* lds, const Gemm g, const Sched& S, const Epi& E) {
;     ...
;             PG8_LDA(At, 1, 1); PG8_STAGE(PG8_SB(1, 0), b3, voffB); PG8_STAGE(PG8_SB(1, 1), b3 + hstep, voffB); PG8_STAGE(PG8_SA(1, 0), a3, voffA);
;             PG8_WAIT_V(8); PG8_WAIT_L(0); PG8_BAR; PG8_MMA(1, 0, At, B0); PG8_MMA(1, 1, At, B1); PG8_BAR; PG8_SCHED;
	s_add_i32 s9, s9, s1
	v_lshl_add_u64 v[196:197], v[196:197], 0, s[52:53]
	s_mov_b32 m0, s9
	ds_read_b128 v[164:167], v251 offset:49152
	ds_read_b128 v[168:171], v251 offset:50176
	ds_read_b128 v[172:175], v251 offset:51200
	ds_read_b128 v[176:179], v251 offset:52224
	ds_read_b128 v[180:183], v251 offset:53248
	ds_read_b128 v[184:187], v251 offset:54272
	ds_read_b128 v[188:191], v251 offset:55296
	ds_read_b128 v[192:195], v251 offset:56320
	global_load_lds_dwordx4 v[196:197], off
	s_add_i32 m0, s9, 0x2000
	s_add_u32 s54, s54, 0xb0080
	v_lshl_add_u64 v[196:197], v[198:199], 0, s[52:53]
	s_addc_u32 s55, s55, 0
	s_add_i32 s9, s71, s1
	global_load_lds_dwordx4 v[196:197], off
	v_lshl_add_u64 v[196:197], s[54:55], 0, v[214:215]
	s_mov_b32 m0, s9
	s_nop 0
	global_load_lds_dwordx4 v[196:197], off
	v_lshl_add_u64 v[196:197], s[54:55], 0, v[218:219]
	s_add_i32 m0, s9, 0x2000
	s_nop 0
	global_load_lds_dwordx4 v[196:197], off
	v_lshl_add_u64 v[196:197], v[200:201], 0, s[52:53]
	s_mov_b32 m0, s63
	s_nop 0
	global_load_lds_dwordx4 v[196:197], off
	v_lshl_add_u64 v[196:197], v[202:203], 0, s[52:53]
	s_mov_b32 m0, s64
	s_nop 0
	global_load_lds_dwordx4 v[196:197], off
	s_waitcnt vmcnt(8)
	s_waitcnt lgkmcnt(0)
	s_barrier
	s_setprio 1
	s_waitcnt lgkmcnt(0)
	v_mfma_f32_16x16x32_bf16 v[64:67], v[124:127], v[164:167], v[64:67]
	v_mfma_f32_16x16x32_bf16 v[60:63], v[132:135], v[164:167], v[60:63]
	v_mfma_f32_16x16x32_bf16 v[48:51], v[124:127], v[172:175], v[48:51]
	v_mfma_f32_16x16x32_bf16 v[44:47], v[132:135], v[172:175], v[44:47]
	v_mfma_f32_16x16x32_bf16 v[32:35], v[124:127], v[180:183], v[32:35]
	v_mfma_f32_16x16x32_bf16 v[28:31], v[132:135], v[180:183], v[28:31]
	v_mfma_f32_16x16x32_bf16 v[16:19], v[124:127], v[188:191], v[16:19]
	v_mfma_f32_16x16x32_bf16 v[12:15], v[132:135], v[188:191], v[12:15]
	v_mfma_f32_16x16x32_bf16 v[64:67], v[128:131], v[168:171], v[64:67]
	v_mfma_f32_16x16x32_bf16 v[60:63], v[136:139], v[168:171], v[60:63]
	v_mfma_f32_16x16x32_bf16 v[48:51], v[128:131], v[176:179], v[48:51]
	v_mfma_f32_16x16x32_bf16 v[44:47], v[136:139], v[176:179], v[44:47]
	v_mfma_f32_16x16x32_bf16 v[32:35], v[128:131], v[184:187], v[32:35]
	v_mfma_f32_16x16x32_bf16 v[28:31], v[136:139], v[184:187], v[28:31]
	v_mfma_f32_16x16x32_bf16 v[16:19], v[128:131], v[192:195], v[16:19]
	v_mfma_f32_16x16x32_bf16 v[12:15], v[136:139], v[192:195], v[12:15]
	s_setprio 0
	s_setprio 1
	v_mfma_f32_16x16x32_bf16 v[56:59], v[148:151], v[164:167], v[56:59]
	v_mfma_f32_16x16x32_bf16 v[52:55], v[156:159], v[164:167], v[52:55]
	v_mfma_f32_16x16x32_bf16 v[40:43], v[148:151], v[172:175], v[40:43]
	v_mfma_f32_16x16x32_bf16 v[36:39], v[156:159], v[172:175], v[36:39]
	v_mfma_f32_16x16x32_bf16 v[24:27], v[148:151], v[180:183], v[24:27]
	v_mfma_f32_16x16x32_bf16 v[20:23], v[156:159], v[180:183], v[20:23]
	v_mfma_f32_16x16x32_bf16 v[8:11], v[148:151], v[188:191], v[8:11]
	v_mfma_f32_16x16x32_bf16 v[4:7], v[156:159], v[188:191], v[4:7]
	v_mfma_f32_16x16x32_bf16 v[56:59], v[152:155], v[168:171], v[56:59]
	v_mfma_f32_16x16x32_bf16 v[52:55], v[160:163], v[168:171], v[52:55]
	v_mfma_f32_16x16x32_bf16 v[40:43], v[152:155], v[176:179], v[40:43]
	v_mfma_f32_16x16x32_bf16 v[36:39], v[160:163], v[176:179], v[36:39]
	v_mfma_f32_16x16x32_bf16 v[24:27], v[152:155], v[184:187], v[24:27]
	v_mfma_f32_16x16x32_bf16 v[20:23], v[160:163], v[184:187], v[20:23]
	v_mfma_f32_16x16x32_bf16 v[8:11], v[152:155], v[192:195], v[8:11]
	v_mfma_f32_16x16x32_bf16 v[4:7], v[160:163], v[192:195], v[4:7]
	s_setprio 0
	s_add_i32 s70, s70, 2
	s_add_u32 s68, s68, 0x100
	s_addc_u32 s69, s69, 0
	s_cmp_gt_u32 s70, 41
	s_mov_b64 s[86:87], s[42:43]
	s_barrier
	s_cbranch_scc0 .LBB0_299
	s_and_b64 vcc, exec, s[36:37]
	s_cbranch_vccz .LBB0_302
	s_barrier

; #define PG8_STAGE(bufoff, gbase, voff) do { _Pragma("unroll") for (int _i = 0; _i < 2; ++_i) \
;         __builtin_amdgcn_global_load_lds((const unsigned*)((const char*)(gbase) + (voff)[_i]), (PG8_LAS unsigned*)(lds + (bufoff) + ldsw + _i * 8192), 16, 0, 0); } while (0)
; #define PG8_LDA(dst, b, h) do { _Pragma("unroll") for (int m = 0; m < 4; ++m) _Pragma("unroll") for (int k = 0; k < 2; ++k) dst[m][k] = *(const PG8_LAS bf16x8*)(lds + PG8_SA(b, h) + aoff + m * 2048 + k * 1024); } while (0)
; #define PG8_LDB(dst, b, h) do { _Pragma("unroll") for (int n = 0; n < 2; ++n) _Pragma("unroll") for (int k = 0; k < 2; ++k) dst[n][k] = *(const PG8_LAS bf16x8*)(lds + PG8_SB(b, h) + boff + n * 2048 + k * 1024); } while (0)
; #define PG8_MMA(ai, bj, At, Bt) do { __builtin_amdgcn_s_setprio(1); _Pragma("unroll") for (int m = 0; m < 4; ++m) _Pragma("unroll") for (int n = 0; n < 2; ++n) _Pragma("unroll") for (int k = 0; k < 2; ++k) \
;         acc[ai][bj][m][n] = __builtin_amdgcn_mfma_f32_16x16x32_bf16(Bt[n][k], At[m][k], acc[ai][bj][m][n], 0, 0, 0); __builtin_amdgcn_s_setprio(0); } while (0)
; #define PG8_WAIT_V(n) asm volatile("s_waitcnt vmcnt(" #n ")" ::: "memory")
; #define PG8_WAIT_L(n) asm volatile("s_waitcnt lgkmcnt(" #n ")" ::: "memory")
; #define PG8_BAR __builtin_amdgcn_s_barrier()
; #define PG8_SCHED __builtin_amdgcn_sched_barrier(0)
; template <class Epi, class Sched, bool ALIGN_EPI = false, bool SP2 = false>
; __device__ __forceinline__ void gemm_phase(PG8_LAS unsigned char* lds, const Gemm g, const Sched& S, const Epi& E) {
;     ...
;             PG8_LDB(B0, 0, 0); PG8_LDB(B1, 0, 1); PG8_SCHED; PG8_LDA(At, 0, 0); PG8_STAGE(PG8_SA(1, 1), a1 + hstep, voffA);
;             PG8_WAIT_V(8); PG8_WAIT_L(0); PG8_BAR; PG8_MMA(0, 0, At, B0); PG8_MMA(0, 1, At, B1); PG8_BAR; PG8_SCHED;
;             PG8_LDA(At, 0, 1); PG8_STAGE(PG8_SB(0, 0), b2, voffB); PG8_STAGE(PG8_SB(0, 1), b2 + hstep, voffB); PG8_STAGE(PG8_SA(0, 0), a2, voffA);
;             PG8_WAIT_V(8); PG8_WAIT_L(0); PG8_BAR; PG8_MMA(1, 0, At, B0); PG8_MMA(1, 1, At, B1); PG8_BAR; PG8_SCHED;
.LBB0_337:
	s_add_u32 s42, s92, 0xfffc0080
	s_addc_u32 s43, s93, -1
	s_add_i32 s58, 0, 0x10000
	s_cmp_eq_u32 s71, 12
	s_cselect_b32 s55, s69, s43
	s_cselect_b32 s54, s85, s42
	v_add_u32_e32 v142, s58, v144
	s_cselect_b32 s43, s37, s70
	s_cselect_b32 s42, vcc_lo, vcc_hi
	s_add_i32 s9, 0, 0x14000
	ds_read_b128 v[148:151], v142
	ds_read_b128 v[152:155], v142 offset:1024
	ds_read_b128 v[156:159], v142 offset:2048
	ds_read_b128 v[160:163], v142 offset:3072
	v_add_u32_e32 v142, s9, v144
	ds_read_b128 v[164:167], v142
	ds_read_b128 v[168:171], v142 offset:1024
	ds_read_b128 v[172:175], v142 offset:2048
	ds_read_b128 v[176:179], v142 offset:3072
	v_lshl_add_u64 v[142:143], s[92:93], 0, v[140:141]
	s_add_i32 m0, s91, 0xc000
	ds_read_b128 v[180:183], v146
	ds_read_b128 v[184:187], v146 offset:1024
	ds_read_b128 v[188:191], v146 offset:2048
	ds_read_b128 v[192:195], v146 offset:3072
	ds_read_b128 v[196:199], v146 offset:4096
	ds_read_b128 v[200:203], v146 offset:5120
	ds_read_b128 v[204:207], v146 offset:6144
	ds_read_b128 v[214:217], v146 offset:7168
	global_load_lds_dwordx4 v[142:143], off
	v_lshl_add_u64 v[142:143], s[92:93], 0, v[138:139]
	s_add_i32 m0, s91, 0xe000
	s_nop 0
	global_load_lds_dwordx4 v[142:143], off
	s_waitcnt vmcnt(8)
	s_waitcnt lgkmcnt(0)
	s_barrier
	s_setprio 1
	s_waitcnt lgkmcnt(0)
	v_mfma_f32_16x16x32_bf16 v[128:131], v[148:151], v[180:183], v[128:131]
	v_mfma_f32_16x16x32_bf16 v[120:123], v[156:159], v[180:183], v[120:123]
	v_mfma_f32_16x16x32_bf16 v[112:115], v[148:151], v[188:191], v[112:115]
	v_mfma_f32_16x16x32_bf16 v[104:107], v[156:159], v[188:191], v[104:107]
	v_mfma_f32_16x16x32_bf16 v[96:99], v[148:151], v[196:199], v[96:99]
	v_mfma_f32_16x16x32_bf16 v[88:91], v[156:159], v[196:199], v[88:91]
	v_mfma_f32_16x16x32_bf16 v[80:83], v[148:151], v[204:207], v[80:83]
	v_mfma_f32_16x16x32_bf16 v[72:75], v[156:159], v[204:207], v[72:75]
	v_mfma_f32_16x16x32_bf16 v[128:131], v[152:155], v[184:187], v[128:131]
	v_mfma_f32_16x16x32_bf16 v[120:123], v[160:163], v[184:187], v[120:123]
	v_mfma_f32_16x16x32_bf16 v[112:115], v[152:155], v[192:195], v[112:115]
	v_mfma_f32_16x16x32_bf16 v[104:107], v[160:163], v[192:195], v[104:107]
	v_mfma_f32_16x16x32_bf16 v[96:99], v[152:155], v[200:203], v[96:99]
	v_mfma_f32_16x16x32_bf16 v[88:91], v[160:163], v[200:203], v[88:91]
	v_mfma_f32_16x16x32_bf16 v[80:83], v[152:155], v[214:217], v[80:83]
	v_mfma_f32_16x16x32_bf16 v[72:75], v[160:163], v[214:217], v[72:75]
	s_setprio 0
	s_setprio 1
	v_mfma_f32_16x16x32_bf16 v[124:127], v[164:167], v[180:183], v[124:127]
	v_mfma_f32_16x16x32_bf16 v[116:119], v[172:175], v[180:183], v[116:119]
	v_mfma_f32_16x16x32_bf16 v[108:111], v[164:167], v[188:191], v[108:111]
	v_mfma_f32_16x16x32_bf16 v[100:103], v[172:175], v[188:191], v[100:103]
	v_mfma_f32_16x16x32_bf16 v[92:95], v[164:167], v[196:199], v[92:95]
	v_mfma_f32_16x16x32_bf16 v[84:87], v[172:175], v[196:199], v[84:87]
	v_mfma_f32_16x16x32_bf16 v[76:79], v[164:167], v[204:207], v[76:79]
	v_mfma_f32_16x16x32_bf16 v[68:71], v[172:175], v[204:207], v[68:71]
	v_mfma_f32_16x16x32_bf16 v[124:127], v[168:171], v[184:187], v[124:127]
	v_mfma_f32_16x16x32_bf16 v[116:119], v[176:179], v[184:187], v[116:119]
	v_mfma_f32_16x16x32_bf16 v[108:111], v[168:171], v[192:195], v[108:111]
	v_mfma_f32_16x16x32_bf16 v[100:103], v[176:179], v[192:195], v[100:103]
	v_mfma_f32_16x16x32_bf16 v[92:95], v[168:171], v[200:203], v[92:95]
	v_mfma_f32_16x16x32_bf16 v[84:87], v[176:179], v[200:203], v[84:87]
	v_mfma_f32_16x16x32_bf16 v[76:79], v[168:171], v[214:217], v[76:79]
	v_mfma_f32_16x16x32_bf16 v[68:71], v[176:179], v[214:217], v[68:71]
	s_setprio 0
	s_barrier
	s_add_i32 s58, s58, s38
	v_lshl_add_u64 v[142:143], s[42:43], 0, v[134:135]
	s_mov_b32 m0, s58
	ds_read_b128 v[180:183], v146 offset:16384
	ds_read_b128 v[184:187], v146 offset:17408
	ds_read_b128 v[188:191], v146 offset:18432
	ds_read_b128 v[192:195], v146 offset:19456
	ds_read_b128 v[196:199], v146 offset:20480
	ds_read_b128 v[200:203], v146 offset:21504
	ds_read_b128 v[204:207], v146 offset:22528
	ds_read_b128 v[214:217], v146 offset:23552
	global_load_lds_dwordx4 v[142:143], off
	s_add_i32 m0, s58, 0x2000
	s_add_u32 s58, s42, 0x40000
	v_lshl_add_u64 v[218:219], s[42:43], 0, v[0:1]
	s_addc_u32 s59, s43, 0
	s_add_i32 s9, s9, s38
	global_load_lds_dwordx4 v[218:219], off
	v_lshl_add_u64 v[220:221], s[58:59], 0, v[134:135]
	s_mov_b32 m0, s9
	v_lshl_add_u64 v[222:223], s[54:55], 0, v[132:133]
	global_load_lds_dwordx4 v[220:221], off
	v_lshl_add_u64 v[220:221], s[58:59], 0, v[0:1]
	s_add_i32 m0, s9, 0x2000
	s_nop 0
	global_load_lds_dwordx4 v[220:221], off
	v_lshl_add_u64 v[220:221], s[54:55], 0, v[136:137]
	s_mov_b32 m0, s91
	s_nop 0
	global_load_lds_dwordx4 v[220:221], off
	s_mov_b32 m0, s45
	s_nop 0
	global_load_lds_dwordx4 v[222:223], off
	s_waitcnt vmcnt(8)
	s_waitcnt lgkmcnt(0)
	s_barrier
; #define PG8_STAGE(bufoff, gbase, voff) do { _Pragma("unroll") for (int _i = 0; _i < 2; ++_i) \
;         __builtin_amdgcn_global_load_lds((const unsigned*)((const char*)(gbase) + (voff)[_i]), (PG8_LAS unsigned*)(lds + (bufoff) + ldsw + _i * 8192), 16, 0, 0); } while (0)
; #define PG8_LDA(dst, b, h) do { _Pragma("unroll") for (int m = 0; m < 4; ++m) _Pragma("unroll") for (int k = 0; k < 2; ++k) dst[m][k] = *(const PG8_LAS bf16x8*)(lds + PG8_SA(b, h) + aoff + m * 2048 + k * 1024); } while (0)
; #define PG8_LDB(dst, b, h) do { _Pragma("unroll") for (int n = 0; n < 2; ++n) _Pragma("unroll") for (int k = 0; k < 2; ++k) dst[n][k] = *(const PG8_LAS bf16x8*)(lds + PG8_SB(b, h) + boff + n * 2048 + k * 1024); } while (0)
; #define PG8_MMA(ai, bj, At, Bt) do { __builtin_amdgcn_s_setprio(1); _Pragma("unroll") for (int m = 0; m < 4; ++m) _Pragma("unroll") for (int n = 0; n < 2; ++n) _Pragma("unroll") for (int k = 0; k < 2; ++k) \
;         acc[ai][bj][m][n] = __builtin_amdgcn_mfma_f32_16x16x32_bf16(Bt[n][k], At[m][k], acc[ai][bj][m][n], 0, 0, 0); __builtin_amdgcn_s_setprio(0); } while (0)
; #define PG8_WAIT_V(n) asm volatile("s_waitcnt vmcnt(" #n ")" ::: "memory")
; #define PG8_WAIT_L(n) asm volatile("s_waitcnt lgkmcnt(" #n ")" ::: "memory")
; #define PG8_BAR __builtin_amdgcn_s_barrier()
; #define PG8_SCHED __builtin_amdgcn_sched_barrier(0)
; template <class Epi, class Sched, bool ALIGN_EPI = false, bool SP2 = false>
; __device__ __forceinline__ void gemm_phase(PG8_LAS unsigned char* lds, const Gemm g, const Sched& S, const Epi& E) {
;     ...
;             PG8_WAIT_V(8); PG8_WAIT_L(0); PG8_BAR; PG8_MMA(1, 0, At, B0); PG8_MMA(1, 1, At, B1); PG8_BAR; PG8_SCHED;
;             PG8_LDB(B0, 1, 0); PG8_LDB(B1, 1, 1); PG8_SCHED; PG8_LDA(At, 1, 0); PG8_STAGE(PG8_SA(0, 1), a2 + hstep, voffA);
;             PG8_WAIT_V(8); PG8_WAIT_L(0); PG8_BAR; PG8_MMA(0, 0, At, B0); PG8_MMA(0, 1, At, B1); PG8_BAR; PG8_SCHED;
	s_setprio 1
	s_waitcnt lgkmcnt(0)
	v_mfma_f32_16x16x32_bf16 v[64:67], v[148:151], v[180:183], v[64:67]
	v_mfma_f32_16x16x32_bf16 v[56:59], v[156:159], v[180:183], v[56:59]
	v_mfma_f32_16x16x32_bf16 v[48:51], v[148:151], v[188:191], v[48:51]
	v_mfma_f32_16x16x32_bf16 v[40:43], v[156:159], v[188:191], v[40:43]
	v_mfma_f32_16x16x32_bf16 v[32:35], v[148:151], v[196:199], v[32:35]
	v_mfma_f32_16x16x32_bf16 v[24:27], v[156:159], v[196:199], v[24:27]
	v_mfma_f32_16x16x32_bf16 v[16:19], v[148:151], v[204:207], v[16:19]
	v_mfma_f32_16x16x32_bf16 v[8:11], v[156:159], v[204:207], v[8:11]
	v_mfma_f32_16x16x32_bf16 v[64:67], v[152:155], v[184:187], v[64:67]
	v_mfma_f32_16x16x32_bf16 v[56:59], v[160:163], v[184:187], v[56:59]
	v_mfma_f32_16x16x32_bf16 v[48:51], v[152:155], v[192:195], v[48:51]
	v_mfma_f32_16x16x32_bf16 v[40:43], v[160:163], v[192:195], v[40:43]
	v_mfma_f32_16x16x32_bf16 v[32:35], v[152:155], v[200:203], v[32:35]
	v_mfma_f32_16x16x32_bf16 v[24:27], v[160:163], v[200:203], v[24:27]
	v_mfma_f32_16x16x32_bf16 v[16:19], v[152:155], v[214:217], v[16:19]
	v_mfma_f32_16x16x32_bf16 v[8:11], v[160:163], v[214:217], v[8:11]
	s_setprio 0
	s_setprio 1
	v_mfma_f32_16x16x32_bf16 v[60:63], v[164:167], v[180:183], v[60:63]
	v_mfma_f32_16x16x32_bf16 v[52:55], v[172:175], v[180:183], v[52:55]
	v_mfma_f32_16x16x32_bf16 v[44:47], v[164:167], v[188:191], v[44:47]
	v_mfma_f32_16x16x32_bf16 v[36:39], v[172:175], v[188:191], v[36:39]
	v_mfma_f32_16x16x32_bf16 v[28:31], v[164:167], v[196:199], v[28:31]
	v_mfma_f32_16x16x32_bf16 v[20:23], v[172:175], v[196:199], v[20:23]
	v_mfma_f32_16x16x32_bf16 v[12:15], v[164:167], v[204:207], v[12:15]
	v_mfma_f32_16x16x32_bf16 v[4:7], v[172:175], v[204:207], v[4:7]
	v_mfma_f32_16x16x32_bf16 v[60:63], v[168:171], v[184:187], v[60:63]
	v_mfma_f32_16x16x32_bf16 v[52:55], v[176:179], v[184:187], v[52:55]
	v_mfma_f32_16x16x32_bf16 v[44:47], v[168:171], v[192:195], v[44:47]
	v_mfma_f32_16x16x32_bf16 v[36:39], v[176:179], v[192:195], v[36:39]
	v_mfma_f32_16x16x32_bf16 v[28:31], v[168:171], v[200:203], v[28:31]
	v_mfma_f32_16x16x32_bf16 v[20:23], v[176:179], v[200:203], v[20:23]
	v_mfma_f32_16x16x32_bf16 v[12:15], v[168:171], v[214:217], v[12:15]
	v_mfma_f32_16x16x32_bf16 v[4:7], v[176:179], v[214:217], v[4:7]
	s_setprio 0
	s_barrier
	s_add_i32 s9, 0, 0x18000
	v_add_u32_e32 v147, s9, v144
	s_add_i32 s58, 0, 0x1c000
	ds_read_b128 v[148:151], v147
	ds_read_b128 v[152:155], v147 offset:1024
	ds_read_b128 v[156:159], v147 offset:2048
	ds_read_b128 v[160:163], v147 offset:3072
	v_add_u32_e32 v147, s58, v144
	ds_read_b128 v[164:167], v147
	ds_read_b128 v[168:171], v147 offset:1024
	ds_read_b128 v[172:175], v147 offset:2048
	ds_read_b128 v[176:179], v147 offset:3072
	s_add_u32 s54, s54, 0x40000
	s_addc_u32 s55, s55, 0
	s_mov_b32 m0, s62
	v_lshl_add_u64 v[224:225], s[54:55], 0, v[136:137]
	ds_read_b128 v[180:183], v146 offset:32768
	ds_read_b128 v[184:187], v146 offset:33792
	ds_read_b128 v[188:191], v146 offset:34816
	ds_read_b128 v[192:195], v146 offset:35840
	ds_read_b128 v[196:199], v146 offset:36864
	ds_read_b128 v[200:203], v146 offset:37888
	ds_read_b128 v[204:207], v146 offset:38912
	ds_read_b128 v[214:217], v146 offset:39936
	global_load_lds_dwordx4 v[224:225], off
	v_lshl_add_u64 v[224:225], s[54:55], 0, v[132:133]
	s_mov_b32 m0, s63
	s_nop 0
	global_load_lds_dwordx4 v[224:225], off
	s_waitcnt vmcnt(8)
	s_waitcnt lgkmcnt(0)
	s_barrier
	s_setprio 1
	s_waitcnt lgkmcnt(0)
	v_mfma_f32_16x16x32_bf16 v[128:131], v[148:151], v[180:183], v[128:131]
	v_mfma_f32_16x16x32_bf16 v[120:123], v[156:159], v[180:183], v[120:123]
	v_mfma_f32_16x16x32_bf16 v[112:115], v[148:151], v[188:191], v[112:115]
	v_mfma_f32_16x16x32_bf16 v[104:107], v[156:159], v[188:191], v[104:107]
	v_mfma_f32_16x16x32_bf16 v[96:99], v[148:151], v[196:199], v[96:99]
	v_mfma_f32_16x16x32_bf16 v[88:91], v[156:159], v[196:199], v[88:91]
	v_mfma_f32_16x16x32_bf16 v[80:83], v[148:151], v[204:207], v[80:83]
	v_mfma_f32_16x16x32_bf16 v[72:75], v[156:159], v[204:207], v[72:75]
	v_mfma_f32_16x16x32_bf16 v[128:131], v[152:155], v[184:187], v[128:131]
	v_mfma_f32_16x16x32_bf16 v[120:123], v[160:163], v[184:187], v[120:123]
	v_mfma_f32_16x16x32_bf16 v[112:115], v[152:155], v[192:195], v[112:115]
	v_mfma_f32_16x16x32_bf16 v[104:107], v[160:163], v[192:195], v[104:107]
	v_mfma_f32_16x16x32_bf16 v[96:99], v[152:155], v[200:203], v[96:99]
	v_mfma_f32_16x16x32_bf16 v[88:91], v[160:163], v[200:203], v[88:91]
	v_mfma_f32_16x16x32_bf16 v[80:83], v[152:155], v[214:217], v[80:83]
	v_mfma_f32_16x16x32_bf16 v[72:75], v[160:163], v[214:217], v[72:75]
	s_setprio 0
	s_setprio 1
	v_mfma_f32_16x16x32_bf16 v[124:127], v[164:167], v[180:183], v[124:127]
	v_mfma_f32_16x16x32_bf16 v[116:119], v[172:175], v[180:183], v[116:119]
	v_mfma_f32_16x16x32_bf16 v[108:111], v[164:167], v[188:191], v[108:111]
	v_mfma_f32_16x16x32_bf16 v[100:103], v[172:175], v[188:191], v[100:103]
	v_mfma_f32_16x16x32_bf16 v[92:95], v[164:167], v[196:199], v[92:95]
	v_mfma_f32_16x16x32_bf16 v[84:87], v[172:175], v[196:199], v[84:87]
	v_mfma_f32_16x16x32_bf16 v[76:79], v[164:167], v[204:207], v[76:79]
	v_mfma_f32_16x16x32_bf16 v[68:71], v[172:175], v[204:207], v[68:71]
	v_mfma_f32_16x16x32_bf16 v[124:127], v[168:171], v[184:187], v[124:127]
	v_mfma_f32_16x16x32_bf16 v[116:119], v[176:179], v[184:187], v[116:119]
	v_mfma_f32_16x16x32_bf16 v[108:111], v[168:171], v[192:195], v[108:111]
	v_mfma_f32_16x16x32_bf16 v[100:103], v[176:179], v[192:195], v[100:103]
	v_mfma_f32_16x16x32_bf16 v[92:95], v[168:171], v[200:203], v[92:95]
	v_mfma_f32_16x16x32_bf16 v[84:87], v[176:179], v[200:203], v[84:87]
	v_mfma_f32_16x16x32_bf16 v[76:79], v[168:171], v[214:217], v[76:79]
	v_mfma_f32_16x16x32_bf16 v[68:71], v[176:179], v[214:217], v[68:71]
	s_setprio 0
	s_barrier
; #define PG8_STAGE(bufoff, gbase, voff) do { _Pragma("unroll") for (int _i = 0; _i < 2; ++_i) \
;         __builtin_amdgcn_global_load_lds((const unsigned*)((const char*)(gbase) + (voff)[_i]), (PG8_LAS unsigned*)(lds + (bufoff) + ldsw + _i * 8192), 16, 0, 0); } while (0)
; #define PG8_LDA(dst, b, h) do { _Pragma("unroll") for (int m = 0; m < 4; ++m) _Pragma("unroll") for (int k = 0; k < 2; ++k) dst[m][k] = *(const PG8_LAS bf16x8*)(lds + PG8_SA(b, h) + aoff + m * 2048 + k * 1024); } while (0)
; #define PG8_MMA(ai, bj, At, Bt) do { __builtin_amdgcn_s_setprio(1); _Pragma("unroll") for (int m = 0; m < 4; ++m) _Pragma("unroll") for (int n = 0; n < 2; ++n) _Pragma("unroll") for (int k = 0; k < 2; ++k) \
;         acc[ai][bj][m][n] = __builtin_amdgcn_mfma_f32_16x16x32_bf16(Bt[n][k], At[m][k], acc[ai][bj][m][n], 0, 0, 0); __builtin_amdgcn_s_setprio(0); } while (0)
; #define PG8_WAIT_V(n) asm volatile("s_waitcnt vmcnt(" #n ")" ::: "memory")
; #define PG8_WAIT_L(n) asm volatile("s_waitcnt lgkmcnt(" #n ")" ::: "memory")
; #define PG8_BAR __builtin_amdgcn_s_barrier()
; #define PG8_SCHED __builtin_amdgcn_sched_barrier(0)
; template <class Epi, class Sched, bool ALIGN_EPI = false, bool SP2 = false>
; __device__ __forceinline__ void gemm_phase(PG8_LAS unsigned char* lds, const Gemm g, const Sched& S, const Epi& E) {
;     ...
;             PG8_LDA(At, 1, 1); PG8_STAGE(PG8_SB(1, 0), b3, voffB); PG8_STAGE(PG8_SB(1, 1), b3 + hstep, voffB); PG8_STAGE(PG8_SA(1, 0), a3, voffA);
;             PG8_WAIT_V(8); PG8_WAIT_L(0); PG8_BAR; PG8_MMA(1, 0, At, B0); PG8_MMA(1, 1, At, B1); PG8_BAR; PG8_SCHED;
	s_add_i32 s9, s9, s38
	v_lshl_add_u64 v[142:143], v[142:143], 0, s[52:53]
	s_mov_b32 m0, s9
	ds_read_b128 v[180:183], v146 offset:49152
	ds_read_b128 v[184:187], v146 offset:50176
	ds_read_b128 v[188:191], v146 offset:51200
	ds_read_b128 v[192:195], v146 offset:52224
	ds_read_b128 v[196:199], v146 offset:53248
	ds_read_b128 v[200:203], v146 offset:54272
	ds_read_b128 v[204:207], v146 offset:55296
	ds_read_b128 v[214:217], v146 offset:56320
	global_load_lds_dwordx4 v[142:143], off
	s_add_i32 m0, s9, 0x2000
	s_add_u32 s42, s42, 0x40080
	v_lshl_add_u64 v[142:143], v[218:219], 0, s[52:53]
	s_addc_u32 s43, s43, 0
	s_add_i32 s9, s58, s38
	global_load_lds_dwordx4 v[142:143], off
	v_lshl_add_u64 v[142:143], s[42:43], 0, v[134:135]
	s_mov_b32 m0, s9
	s_nop 0
	global_load_lds_dwordx4 v[142:143], off
	v_lshl_add_u64 v[142:143], s[42:43], 0, v[0:1]
	s_add_i32 m0, s9, 0x2000
	s_nop 0
	global_load_lds_dwordx4 v[142:143], off
	v_lshl_add_u64 v[142:143], v[220:221], 0, s[52:53]
	s_mov_b32 m0, s64
	s_nop 0
	global_load_lds_dwordx4 v[142:143], off
	v_lshl_add_u64 v[142:143], v[222:223], 0, s[52:53]
	s_mov_b32 m0, s65
	s_nop 0
	global_load_lds_dwordx4 v[142:143], off
	s_waitcnt vmcnt(8)
	s_waitcnt lgkmcnt(0)
	s_barrier
	s_setprio 1
	s_waitcnt lgkmcnt(0)
	v_mfma_f32_16x16x32_bf16 v[64:67], v[148:151], v[180:183], v[64:67]
	v_mfma_f32_16x16x32_bf16 v[56:59], v[156:159], v[180:183], v[56:59]
	v_mfma_f32_16x16x32_bf16 v[48:51], v[148:151], v[188:191], v[48:51]
	v_mfma_f32_16x16x32_bf16 v[40:43], v[156:159], v[188:191], v[40:43]
	v_mfma_f32_16x16x32_bf16 v[32:35], v[148:151], v[196:199], v[32:35]
	v_mfma_f32_16x16x32_bf16 v[24:27], v[156:159], v[196:199], v[24:27]
	v_mfma_f32_16x16x32_bf16 v[16:19], v[148:151], v[204:207], v[16:19]
	v_mfma_f32_16x16x32_bf16 v[8:11], v[156:159], v[204:207], v[8:11]
	v_mfma_f32_16x16x32_bf16 v[64:67], v[152:155], v[184:187], v[64:67]
	v_mfma_f32_16x16x32_bf16 v[56:59], v[160:163], v[184:187], v[56:59]
	v_mfma_f32_16x16x32_bf16 v[48:51], v[152:155], v[192:195], v[48:51]
	v_mfma_f32_16x16x32_bf16 v[40:43], v[160:163], v[192:195], v[40:43]
	v_mfma_f32_16x16x32_bf16 v[32:35], v[152:155], v[200:203], v[32:35]
	v_mfma_f32_16x16x32_bf16 v[24:27], v[160:163], v[200:203], v[24:27]
	v_mfma_f32_16x16x32_bf16 v[16:19], v[152:155], v[214:217], v[16:19]
	v_mfma_f32_16x16x32_bf16 v[8:11], v[160:163], v[214:217], v[8:11]
	s_setprio 0
	s_setprio 1
	v_mfma_f32_16x16x32_bf16 v[60:63], v[164:167], v[180:183], v[60:63]
	v_mfma_f32_16x16x32_bf16 v[52:55], v[172:175], v[180:183], v[52:55]
	v_mfma_f32_16x16x32_bf16 v[44:47], v[164:167], v[188:191], v[44:47]
	v_mfma_f32_16x16x32_bf16 v[36:39], v[172:175], v[188:191], v[36:39]
	v_mfma_f32_16x16x32_bf16 v[28:31], v[164:167], v[196:199], v[28:31]
	v_mfma_f32_16x16x32_bf16 v[20:23], v[172:175], v[196:199], v[20:23]
	v_mfma_f32_16x16x32_bf16 v[12:15], v[164:167], v[204:207], v[12:15]
	v_mfma_f32_16x16x32_bf16 v[4:7], v[172:175], v[204:207], v[4:7]
	v_mfma_f32_16x16x32_bf16 v[60:63], v[168:171], v[184:187], v[60:63]
	v_mfma_f32_16x16x32_bf16 v[52:55], v[176:179], v[184:187], v[52:55]
	v_mfma_f32_16x16x32_bf16 v[44:47], v[168:171], v[192:195], v[44:47]
	v_mfma_f32_16x16x32_bf16 v[36:39], v[176:179], v[192:195], v[36:39]
	v_mfma_f32_16x16x32_bf16 v[28:31], v[168:171], v[200:203], v[28:31]
	v_mfma_f32_16x16x32_bf16 v[20:23], v[176:179], v[200:203], v[20:23]
	v_mfma_f32_16x16x32_bf16 v[12:15], v[168:171], v[214:217], v[12:15]
	v_mfma_f32_16x16x32_bf16 v[4:7], v[176:179], v[214:217], v[4:7]
	s_setprio 0
	s_add_i32 s71, s71, 2
	s_add_u32 vcc_hi, vcc_hi, 0x100
	s_addc_u32 s70, s70, 0
	s_add_u32 s92, s92, 0x100
	s_addc_u32 s93, s93, 0
	s_cmp_gt_u32 s71, 13
	s_barrier
	s_cbranch_scc0 .LBB0_337
	s_and_b64 vcc, exec, s[34:35]
	s_cbranch_vccz .LBB0_340
	s_barrier

; #define PG8_STAGE(bufoff, gbase, voff) do { _Pragma("unroll") for (int _i = 0; _i < 2; ++_i) \
;         __builtin_amdgcn_global_load_lds((const unsigned*)((const char*)(gbase) + (voff)[_i]), (PG8_LAS unsigned*)(lds + (bufoff) + ldsw + _i * 8192), 16, 0, 0); } while (0)
; #define PG8_LDA(dst, b, h) do { _Pragma("unroll") for (int m = 0; m < 4; ++m) _Pragma("unroll") for (int k = 0; k < 2; ++k) dst[m][k] = *(const PG8_LAS bf16x8*)(lds + PG8_SA(b, h) + aoff + m * 2048 + k * 1024); } while (0)
; #define PG8_LDB(dst, b, h) do { _Pragma("unroll") for (int n = 0; n < 2; ++n) _Pragma("unroll") for (int k = 0; k < 2; ++k) dst[n][k] = *(const PG8_LAS bf16x8*)(lds + PG8_SB(b, h) + boff + n * 2048 + k * 1024); } while (0)
; #define PG8_MMA(ai, bj, At, Bt) do { __builtin_amdgcn_s_setprio(1); _Pragma("unroll") for (int m = 0; m < 4; ++m) _Pragma("unroll") for (int n = 0; n < 2; ++n) _Pragma("unroll") for (int k = 0; k < 2; ++k) \
;         acc[ai][bj][m][n] = __builtin_amdgcn_mfma_f32_16x16x32_bf16(Bt[n][k], At[m][k], acc[ai][bj][m][n], 0, 0, 0); __builtin_amdgcn_s_setprio(0); } while (0)
; #define PG8_WAIT_V(n) asm volatile("s_waitcnt vmcnt(" #n ")" ::: "memory")
; #define PG8_WAIT_L(n) asm volatile("s_waitcnt lgkmcnt(" #n ")" ::: "memory")
; #define PG8_BAR __builtin_amdgcn_s_barrier()
; #define PG8_SCHED __builtin_amdgcn_sched_barrier(0)
; template <class Epi, class Sched, bool ALIGN_EPI = false, bool SP2 = false>
; __device__ __forceinline__ void gemm_phase(PG8_LAS unsigned char* lds, const Gemm g, const Sched& S, const Epi& E) {
;     ...
;             PG8_LDB(B0, 0, 0); PG8_LDB(B1, 0, 1); PG8_SCHED; PG8_LDA(At, 0, 0); PG8_STAGE(PG8_SA(1, 1), a1 + hstep, voffA);
;             PG8_WAIT_V(8); PG8_WAIT_L(0); PG8_BAR; PG8_MMA(0, 0, At, B0); PG8_MMA(0, 1, At, B1); PG8_BAR; PG8_SCHED;
;             PG8_LDA(At, 0, 1); PG8_STAGE(PG8_SB(0, 0), b2, voffB); PG8_STAGE(PG8_SB(0, 1), b2 + hstep, voffB); PG8_STAGE(PG8_SA(0, 0), a2, voffA);
;             PG8_WAIT_V(8); PG8_WAIT_L(0); PG8_BAR; PG8_MMA(1, 0, At, B0); PG8_MMA(1, 1, At, B1); PG8_BAR; PG8_SCHED;
.LBB0_428:
	s_add_u32 s42, s92, 0xfffc0080
	s_addc_u32 s43, s93, -1
	s_add_i32 s58, 0, 0x10000
	s_cmp_eq_u32 s70, 12
	s_cselect_b32 s55, s67, s43
	s_cselect_b32 s54, s68, s42
	s_cselect_b32 s43, s37, s83
	s_cselect_b32 s42, s69, s82
	s_add_i32 s59, 0, 0x14000
	v_add_u32_e32 v136, s58, v213
	v_add_u32_e32 v160, s59, v213
	ds_read_b128 v[124:127], v136
	ds_read_b128 v[128:131], v136 offset:1024
	ds_read_b128 v[132:135], v136 offset:2048
	ds_read_b128 v[136:139], v136 offset:3072
	ds_read_b128 v[148:151], v160
	ds_read_b128 v[152:155], v160 offset:1024
	ds_read_b128 v[156:159], v160 offset:2048
	ds_read_b128 v[160:163], v160 offset:3072
	v_lshl_add_u64 v[196:197], s[92:93], 0, v[222:223]
	s_add_i32 m0, s3, 0xc000
	ds_read_b128 v[164:167], v251
	ds_read_b128 v[168:171], v251 offset:1024
	ds_read_b128 v[172:175], v251 offset:2048
	ds_read_b128 v[176:179], v251 offset:3072
	ds_read_b128 v[180:183], v251 offset:4096
	ds_read_b128 v[184:187], v251 offset:5120
	ds_read_b128 v[188:191], v251 offset:6144
	ds_read_b128 v[192:195], v251 offset:7168
	global_load_lds_dwordx4 v[196:197], off
	v_lshl_add_u64 v[196:197], s[92:93], 0, v[220:221]
	s_add_i32 m0, s3, 0xe000
	s_nop 0
	global_load_lds_dwordx4 v[196:197], off
	s_waitcnt vmcnt(8)
	s_waitcnt lgkmcnt(0)
	s_barrier
	s_setprio 1
	s_waitcnt lgkmcnt(0)
	v_mfma_f32_16x16x32_bf16 v[144:147], v[124:127], v[164:167], v[144:147]
	v_mfma_f32_16x16x32_bf16 v[140:143], v[132:135], v[164:167], v[140:143]
	v_mfma_f32_16x16x32_bf16 v[112:115], v[124:127], v[172:175], v[112:115]
	v_mfma_f32_16x16x32_bf16 v[108:111], v[132:135], v[172:175], v[108:111]
	v_mfma_f32_16x16x32_bf16 v[96:99], v[124:127], v[180:183], v[96:99]
	v_mfma_f32_16x16x32_bf16 v[92:95], v[132:135], v[180:183], v[92:95]
	v_mfma_f32_16x16x32_bf16 v[80:83], v[124:127], v[188:191], v[80:83]
	v_mfma_f32_16x16x32_bf16 v[76:79], v[132:135], v[188:191], v[76:79]
	v_mfma_f32_16x16x32_bf16 v[144:147], v[128:131], v[168:171], v[144:147]
	v_mfma_f32_16x16x32_bf16 v[140:143], v[136:139], v[168:171], v[140:143]
	v_mfma_f32_16x16x32_bf16 v[112:115], v[128:131], v[176:179], v[112:115]
	v_mfma_f32_16x16x32_bf16 v[108:111], v[136:139], v[176:179], v[108:111]
	v_mfma_f32_16x16x32_bf16 v[96:99], v[128:131], v[184:187], v[96:99]
	v_mfma_f32_16x16x32_bf16 v[92:95], v[136:139], v[184:187], v[92:95]
	v_mfma_f32_16x16x32_bf16 v[80:83], v[128:131], v[192:195], v[80:83]
	v_mfma_f32_16x16x32_bf16 v[76:79], v[136:139], v[192:195], v[76:79]
	s_setprio 0
	s_setprio 1
	v_mfma_f32_16x16x32_bf16 v[120:123], v[148:151], v[164:167], v[120:123]
	v_mfma_f32_16x16x32_bf16 v[116:119], v[156:159], v[164:167], v[116:119]
	v_mfma_f32_16x16x32_bf16 v[104:107], v[148:151], v[172:175], v[104:107]
	v_mfma_f32_16x16x32_bf16 v[100:103], v[156:159], v[172:175], v[100:103]
	v_mfma_f32_16x16x32_bf16 v[88:91], v[148:151], v[180:183], v[88:91]
	v_mfma_f32_16x16x32_bf16 v[84:87], v[156:159], v[180:183], v[84:87]
	v_mfma_f32_16x16x32_bf16 v[72:75], v[148:151], v[188:191], v[72:75]
	v_mfma_f32_16x16x32_bf16 v[68:71], v[156:159], v[188:191], v[68:71]
	v_mfma_f32_16x16x32_bf16 v[120:123], v[152:155], v[168:171], v[120:123]
	v_mfma_f32_16x16x32_bf16 v[116:119], v[160:163], v[168:171], v[116:119]
	v_mfma_f32_16x16x32_bf16 v[104:107], v[152:155], v[176:179], v[104:107]
	v_mfma_f32_16x16x32_bf16 v[100:103], v[160:163], v[176:179], v[100:103]
	v_mfma_f32_16x16x32_bf16 v[88:91], v[152:155], v[184:187], v[88:91]
	v_mfma_f32_16x16x32_bf16 v[84:87], v[160:163], v[184:187], v[84:87]
	v_mfma_f32_16x16x32_bf16 v[72:75], v[152:155], v[192:195], v[72:75]
	v_mfma_f32_16x16x32_bf16 v[68:71], v[160:163], v[192:195], v[68:71]
	s_setprio 0
	s_barrier
	s_add_i32 s58, s58, s1
	v_lshl_add_u64 v[196:197], s[42:43], 0, v[214:215]
	s_mov_b32 m0, s58
	ds_read_b128 v[164:167], v251 offset:16384
	ds_read_b128 v[168:171], v251 offset:17408
	ds_read_b128 v[172:175], v251 offset:18432
	ds_read_b128 v[176:179], v251 offset:19456
	ds_read_b128 v[180:183], v251 offset:20480
	ds_read_b128 v[184:187], v251 offset:21504
	ds_read_b128 v[188:191], v251 offset:22528
	ds_read_b128 v[192:195], v251 offset:23552
	global_load_lds_dwordx4 v[196:197], off
	s_add_i32 m0, s58, 0x2000
	s_add_u32 s94, s42, 0x40000
	v_lshl_add_u64 v[198:199], s[42:43], 0, v[218:219]
	s_addc_u32 s95, s43, 0
	s_add_i32 s58, s59, s1
	global_load_lds_dwordx4 v[198:199], off
	v_lshl_add_u64 v[200:201], s[94:95], 0, v[214:215]
	s_mov_b32 m0, s58
	v_lshl_add_u64 v[202:203], s[54:55], 0, v[216:217]
	global_load_lds_dwordx4 v[200:201], off
	v_lshl_add_u64 v[200:201], s[94:95], 0, v[218:219]
	s_add_i32 m0, s58, 0x2000
	s_nop 0
	global_load_lds_dwordx4 v[200:201], off
	v_lshl_add_u64 v[200:201], s[54:55], 0, v[0:1]
	s_mov_b32 m0, s3
	s_nop 0
	global_load_lds_dwordx4 v[200:201], off
	s_mov_b32 m0, s8
	s_nop 0
	global_load_lds_dwordx4 v[202:203], off
	s_waitcnt vmcnt(8)
	s_waitcnt lgkmcnt(0)
	s_barrier
; #define PG8_STAGE(bufoff, gbase, voff) do { _Pragma("unroll") for (int _i = 0; _i < 2; ++_i) \
;         __builtin_amdgcn_global_load_lds((const unsigned*)((const char*)(gbase) + (voff)[_i]), (PG8_LAS unsigned*)(lds + (bufoff) + ldsw + _i * 8192), 16, 0, 0); } while (0)
; #define PG8_LDA(dst, b, h) do { _Pragma("unroll") for (int m = 0; m < 4; ++m) _Pragma("unroll") for (int k = 0; k < 2; ++k) dst[m][k] = *(const PG8_LAS bf16x8*)(lds + PG8_SA(b, h) + aoff + m * 2048 + k * 1024); } while (0)
; #define PG8_LDB(dst, b, h) do { _Pragma("unroll") for (int n = 0; n < 2; ++n) _Pragma("unroll") for (int k = 0; k < 2; ++k) dst[n][k] = *(const PG8_LAS bf16x8*)(lds + PG8_SB(b, h) + boff + n * 2048 + k * 1024); } while (0)
; #define PG8_MMA(ai, bj, At, Bt) do { __builtin_amdgcn_s_setprio(1); _Pragma("unroll") for (int m = 0; m < 4; ++m) _Pragma("unroll") for (int n = 0; n < 2; ++n) _Pragma("unroll") for (int k = 0; k < 2; ++k) \
;         acc[ai][bj][m][n] = __builtin_amdgcn_mfma_f32_16x16x32_bf16(Bt[n][k], At[m][k], acc[ai][bj][m][n], 0, 0, 0); __builtin_amdgcn_s_setprio(0); } while (0)
; #define PG8_WAIT_V(n) asm volatile("s_waitcnt vmcnt(" #n ")" ::: "memory")
; #define PG8_WAIT_L(n) asm volatile("s_waitcnt lgkmcnt(" #n ")" ::: "memory")
; #define PG8_BAR __builtin_amdgcn_s_barrier()
; #define PG8_SCHED __builtin_amdgcn_sched_barrier(0)
; template <class Epi, class Sched, bool ALIGN_EPI = false, bool SP2 = false>
; __device__ __forceinline__ void gemm_phase(PG8_LAS unsigned char* lds, const Gemm g, const Sched& S, const Epi& E) {
;     ...
;             PG8_WAIT_V(8); PG8_WAIT_L(0); PG8_BAR; PG8_MMA(1, 0, At, B0); PG8_MMA(1, 1, At, B1); PG8_BAR; PG8_SCHED;
;             PG8_LDB(B0, 1, 0); PG8_LDB(B1, 1, 1); PG8_SCHED; PG8_LDA(At, 1, 0); PG8_STAGE(PG8_SA(0, 1), a2 + hstep, voffA);
;             PG8_WAIT_V(8); PG8_WAIT_L(0); PG8_BAR; PG8_MMA(0, 0, At, B0); PG8_MMA(0, 1, At, B1); PG8_BAR; PG8_SCHED;
	s_setprio 1
	s_waitcnt lgkmcnt(0)
	v_mfma_f32_16x16x32_bf16 v[64:67], v[124:127], v[164:167], v[64:67]
	v_mfma_f32_16x16x32_bf16 v[60:63], v[132:135], v[164:167], v[60:63]
	v_mfma_f32_16x16x32_bf16 v[48:51], v[124:127], v[172:175], v[48:51]
	v_mfma_f32_16x16x32_bf16 v[44:47], v[132:135], v[172:175], v[44:47]
	v_mfma_f32_16x16x32_bf16 v[32:35], v[124:127], v[180:183], v[32:35]
	v_mfma_f32_16x16x32_bf16 v[28:31], v[132:135], v[180:183], v[28:31]
	v_mfma_f32_16x16x32_bf16 v[16:19], v[124:127], v[188:191], v[16:19]
	v_mfma_f32_16x16x32_bf16 v[12:15], v[132:135], v[188:191], v[12:15]
	v_mfma_f32_16x16x32_bf16 v[64:67], v[128:131], v[168:171], v[64:67]
	v_mfma_f32_16x16x32_bf16 v[60:63], v[136:139], v[168:171], v[60:63]
	v_mfma_f32_16x16x32_bf16 v[48:51], v[128:131], v[176:179], v[48:51]
	v_mfma_f32_16x16x32_bf16 v[44:47], v[136:139], v[176:179], v[44:47]
	v_mfma_f32_16x16x32_bf16 v[32:35], v[128:131], v[184:187], v[32:35]
	v_mfma_f32_16x16x32_bf16 v[28:31], v[136:139], v[184:187], v[28:31]
	v_mfma_f32_16x16x32_bf16 v[16:19], v[128:131], v[192:195], v[16:19]
	v_mfma_f32_16x16x32_bf16 v[12:15], v[136:139], v[192:195], v[12:15]
	s_setprio 0
	s_setprio 1
	v_mfma_f32_16x16x32_bf16 v[56:59], v[148:151], v[164:167], v[56:59]
	v_mfma_f32_16x16x32_bf16 v[52:55], v[156:159], v[164:167], v[52:55]
	v_mfma_f32_16x16x32_bf16 v[40:43], v[148:151], v[172:175], v[40:43]
	v_mfma_f32_16x16x32_bf16 v[36:39], v[156:159], v[172:175], v[36:39]
	v_mfma_f32_16x16x32_bf16 v[24:27], v[148:151], v[180:183], v[24:27]
	v_mfma_f32_16x16x32_bf16 v[20:23], v[156:159], v[180:183], v[20:23]
	v_mfma_f32_16x16x32_bf16 v[8:11], v[148:151], v[188:191], v[8:11]
	v_mfma_f32_16x16x32_bf16 v[4:7], v[156:159], v[188:191], v[4:7]
	v_mfma_f32_16x16x32_bf16 v[56:59], v[152:155], v[168:171], v[56:59]
	v_mfma_f32_16x16x32_bf16 v[52:55], v[160:163], v[168:171], v[52:55]
	v_mfma_f32_16x16x32_bf16 v[40:43], v[152:155], v[176:179], v[40:43]
	v_mfma_f32_16x16x32_bf16 v[36:39], v[160:163], v[176:179], v[36:39]
	v_mfma_f32_16x16x32_bf16 v[24:27], v[152:155], v[184:187], v[24:27]
	v_mfma_f32_16x16x32_bf16 v[20:23], v[160:163], v[184:187], v[20:23]
	v_mfma_f32_16x16x32_bf16 v[8:11], v[152:155], v[192:195], v[8:11]
	v_mfma_f32_16x16x32_bf16 v[4:7], v[160:163], v[192:195], v[4:7]
	s_setprio 0
	s_barrier
	s_add_i32 s58, 0, 0x18000
	s_add_i32 s59, 0, 0x1c000
	v_add_u32_e32 v136, s58, v213
	v_add_u32_e32 v160, s59, v213
	ds_read_b128 v[124:127], v136
	ds_read_b128 v[128:131], v136 offset:1024
	ds_read_b128 v[132:135], v136 offset:2048
	ds_read_b128 v[136:139], v136 offset:3072
	ds_read_b128 v[148:151], v160
	ds_read_b128 v[152:155], v160 offset:1024
	ds_read_b128 v[156:159], v160 offset:2048
	ds_read_b128 v[160:163], v160 offset:3072
	s_add_u32 s54, s54, 0x40000
	s_addc_u32 s55, s55, 0
	s_mov_b32 m0, s23
	v_lshl_add_u64 v[204:205], s[54:55], 0, v[0:1]
	ds_read_b128 v[164:167], v251 offset:32768
	ds_read_b128 v[168:171], v251 offset:33792
	ds_read_b128 v[172:175], v251 offset:34816
	ds_read_b128 v[176:179], v251 offset:35840
	ds_read_b128 v[180:183], v251 offset:36864
	ds_read_b128 v[184:187], v251 offset:37888
	ds_read_b128 v[188:191], v251 offset:38912
	ds_read_b128 v[192:195], v251 offset:39936
	global_load_lds_dwordx4 v[204:205], off
	v_lshl_add_u64 v[204:205], s[54:55], 0, v[216:217]
	s_mov_b32 m0, s38
	s_nop 0
	global_load_lds_dwordx4 v[204:205], off
	s_waitcnt vmcnt(8)
	s_waitcnt lgkmcnt(0)
	s_barrier
	s_setprio 1
	s_waitcnt lgkmcnt(0)
	v_mfma_f32_16x16x32_bf16 v[144:147], v[124:127], v[164:167], v[144:147]
	v_mfma_f32_16x16x32_bf16 v[140:143], v[132:135], v[164:167], v[140:143]
	v_mfma_f32_16x16x32_bf16 v[112:115], v[124:127], v[172:175], v[112:115]
	v_mfma_f32_16x16x32_bf16 v[108:111], v[132:135], v[172:175], v[108:111]
	v_mfma_f32_16x16x32_bf16 v[96:99], v[124:127], v[180:183], v[96:99]
	v_mfma_f32_16x16x32_bf16 v[92:95], v[132:135], v[180:183], v[92:95]
	v_mfma_f32_16x16x32_bf16 v[80:83], v[124:127], v[188:191], v[80:83]
	v_mfma_f32_16x16x32_bf16 v[76:79], v[132:135], v[188:191], v[76:79]
	v_mfma_f32_16x16x32_bf16 v[144:147], v[128:131], v[168:171], v[144:147]
	v_mfma_f32_16x16x32_bf16 v[140:143], v[136:139], v[168:171], v[140:143]
	v_mfma_f32_16x16x32_bf16 v[112:115], v[128:131], v[176:179], v[112:115]
	v_mfma_f32_16x16x32_bf16 v[108:111], v[136:139], v[176:179], v[108:111]
	v_mfma_f32_16x16x32_bf16 v[96:99], v[128:131], v[184:187], v[96:99]
	v_mfma_f32_16x16x32_bf16 v[92:95], v[136:139], v[184:187], v[92:95]
	v_mfma_f32_16x16x32_bf16 v[80:83], v[128:131], v[192:195], v[80:83]
	v_mfma_f32_16x16x32_bf16 v[76:79], v[136:139], v[192:195], v[76:79]
	s_setprio 0
	s_setprio 1
	v_mfma_f32_16x16x32_bf16 v[120:123], v[148:151], v[164:167], v[120:123]
	v_mfma_f32_16x16x32_bf16 v[116:119], v[156:159], v[164:167], v[116:119]
	v_mfma_f32_16x16x32_bf16 v[104:107], v[148:151], v[172:175], v[104:107]
	v_mfma_f32_16x16x32_bf16 v[100:103], v[156:159], v[172:175], v[100:103]
	v_mfma_f32_16x16x32_bf16 v[88:91], v[148:151], v[180:183], v[88:91]
	v_mfma_f32_16x16x32_bf16 v[84:87], v[156:159], v[180:183], v[84:87]
	v_mfma_f32_16x16x32_bf16 v[72:75], v[148:151], v[188:191], v[72:75]
	v_mfma_f32_16x16x32_bf16 v[68:71], v[156:159], v[188:191], v[68:71]
	v_mfma_f32_16x16x32_bf16 v[120:123], v[152:155], v[168:171], v[120:123]
	v_mfma_f32_16x16x32_bf16 v[116:119], v[160:163], v[168:171], v[116:119]
	v_mfma_f32_16x16x32_bf16 v[104:107], v[152:155], v[176:179], v[104:107]
	v_mfma_f32_16x16x32_bf16 v[100:103], v[160:163], v[176:179], v[100:103]
	v_mfma_f32_16x16x32_bf16 v[88:91], v[152:155], v[184:187], v[88:91]
	v_mfma_f32_16x16x32_bf16 v[84:87], v[160:163], v[184:187], v[84:87]
	v_mfma_f32_16x16x32_bf16 v[72:75], v[152:155], v[192:195], v[72:75]
	v_mfma_f32_16x16x32_bf16 v[68:71], v[160:163], v[192:195], v[68:71]
	s_setprio 0
	s_barrier
; #define PG8_STAGE(bufoff, gbase, voff) do { _Pragma("unroll") for (int _i = 0; _i < 2; ++_i) \
;         __builtin_amdgcn_global_load_lds((const unsigned*)((const char*)(gbase) + (voff)[_i]), (PG8_LAS unsigned*)(lds + (bufoff) + ldsw + _i * 8192), 16, 0, 0); } while (0)
; #define PG8_LDA(dst, b, h) do { _Pragma("unroll") for (int m = 0; m < 4; ++m) _Pragma("unroll") for (int k = 0; k < 2; ++k) dst[m][k] = *(const PG8_LAS bf16x8*)(lds + PG8_SA(b, h) + aoff + m * 2048 + k * 1024); } while (0)
; #define PG8_MMA(ai, bj, At, Bt) do { __builtin_amdgcn_s_setprio(1); _Pragma("unroll") for (int m = 0; m < 4; ++m) _Pragma("unroll") for (int n = 0; n < 2; ++n) _Pragma("unroll") for (int k = 0; k < 2; ++k) \
;         acc[ai][bj][m][n] = __builtin_amdgcn_mfma_f32_16x16x32_bf16(Bt[n][k], At[m][k], acc[ai][bj][m][n], 0, 0, 0); __builtin_amdgcn_s_setprio(0); } while (0)
; #define PG8_WAIT_V(n) asm volatile("s_waitcnt vmcnt(" #n ")" ::: "memory")
; #define PG8_WAIT_L(n) asm volatile("s_waitcnt lgkmcnt(" #n ")" ::: "memory")
; #define PG8_BAR __builtin_amdgcn_s_barrier()
; #define PG8_SCHED __builtin_amdgcn_sched_barrier(0)
; template <class Epi, class Sched, bool ALIGN_EPI = false, bool SP2 = false>
; __device__ __forceinline__ void gemm_phase(PG8_LAS unsigned char* lds, const Gemm g, const Sched& S, const Epi& E) {
;     ...
;             PG8_LDA(At, 1, 1); PG8_STAGE(PG8_SB(1, 0), b3, voffB); PG8_STAGE(PG8_SB(1, 1), b3 + hstep, voffB); PG8_STAGE(PG8_SA(1, 0), a3, voffA);
;             PG8_WAIT_V(8); PG8_WAIT_L(0); PG8_BAR; PG8_MMA(1, 0, At, B0); PG8_MMA(1, 1, At, B1); PG8_BAR; PG8_SCHED;
	s_add_i32 s54, s58, s1
	v_lshl_add_u64 v[196:197], v[196:197], 0, s[52:53]
	s_mov_b32 m0, s54
	ds_read_b128 v[164:167], v251 offset:49152
	ds_read_b128 v[168:171], v251 offset:50176
	ds_read_b128 v[172:175], v251 offset:51200
	ds_read_b128 v[176:179], v251 offset:52224
	ds_read_b128 v[180:183], v251 offset:53248
	ds_read_b128 v[184:187], v251 offset:54272
	ds_read_b128 v[188:191], v251 offset:55296
	ds_read_b128 v[192:195], v251 offset:56320
	global_load_lds_dwordx4 v[196:197], off
	s_add_i32 m0, s54, 0x2000
	s_add_u32 s42, s42, 0x40080
	v_lshl_add_u64 v[196:197], v[198:199], 0, s[52:53]
	s_addc_u32 s43, s43, 0
	s_add_i32 s54, s59, s1
	global_load_lds_dwordx4 v[196:197], off
	v_lshl_add_u64 v[196:197], s[42:43], 0, v[214:215]
	s_mov_b32 m0, s54
	s_nop 0
	global_load_lds_dwordx4 v[196:197], off
	v_lshl_add_u64 v[196:197], s[42:43], 0, v[218:219]
	s_add_i32 m0, s54, 0x2000
	s_nop 0
	global_load_lds_dwordx4 v[196:197], off
	v_lshl_add_u64 v[196:197], v[200:201], 0, s[52:53]
	s_mov_b32 m0, s62
	s_nop 0
	global_load_lds_dwordx4 v[196:197], off
	v_lshl_add_u64 v[196:197], v[202:203], 0, s[52:53]
	s_mov_b32 m0, s63
	s_nop 0
	global_load_lds_dwordx4 v[196:197], off
	s_waitcnt vmcnt(8)
	s_waitcnt lgkmcnt(0)
	s_barrier
	s_setprio 1
	s_waitcnt lgkmcnt(0)
	v_mfma_f32_16x16x32_bf16 v[64:67], v[124:127], v[164:167], v[64:67]
	v_mfma_f32_16x16x32_bf16 v[60:63], v[132:135], v[164:167], v[60:63]
	v_mfma_f32_16x16x32_bf16 v[48:51], v[124:127], v[172:175], v[48:51]
	v_mfma_f32_16x16x32_bf16 v[44:47], v[132:135], v[172:175], v[44:47]
	v_mfma_f32_16x16x32_bf16 v[32:35], v[124:127], v[180:183], v[32:35]
	v_mfma_f32_16x16x32_bf16 v[28:31], v[132:135], v[180:183], v[28:31]
	v_mfma_f32_16x16x32_bf16 v[16:19], v[124:127], v[188:191], v[16:19]
	v_mfma_f32_16x16x32_bf16 v[12:15], v[132:135], v[188:191], v[12:15]
	v_mfma_f32_16x16x32_bf16 v[64:67], v[128:131], v[168:171], v[64:67]
	v_mfma_f32_16x16x32_bf16 v[60:63], v[136:139], v[168:171], v[60:63]
	v_mfma_f32_16x16x32_bf16 v[48:51], v[128:131], v[176:179], v[48:51]
	v_mfma_f32_16x16x32_bf16 v[44:47], v[136:139], v[176:179], v[44:47]
	v_mfma_f32_16x16x32_bf16 v[32:35], v[128:131], v[184:187], v[32:35]
	v_mfma_f32_16x16x32_bf16 v[28:31], v[136:139], v[184:187], v[28:31]
	v_mfma_f32_16x16x32_bf16 v[16:19], v[128:131], v[192:195], v[16:19]
	v_mfma_f32_16x16x32_bf16 v[12:15], v[136:139], v[192:195], v[12:15]
	s_setprio 0
	s_setprio 1
	v_mfma_f32_16x16x32_bf16 v[56:59], v[148:151], v[164:167], v[56:59]
	v_mfma_f32_16x16x32_bf16 v[52:55], v[156:159], v[164:167], v[52:55]
	v_mfma_f32_16x16x32_bf16 v[40:43], v[148:151], v[172:175], v[40:43]
	v_mfma_f32_16x16x32_bf16 v[36:39], v[156:159], v[172:175], v[36:39]
	v_mfma_f32_16x16x32_bf16 v[24:27], v[148:151], v[180:183], v[24:27]
	v_mfma_f32_16x16x32_bf16 v[20:23], v[156:159], v[180:183], v[20:23]
	v_mfma_f32_16x16x32_bf16 v[8:11], v[148:151], v[188:191], v[8:11]
	v_mfma_f32_16x16x32_bf16 v[4:7], v[156:159], v[188:191], v[4:7]
	v_mfma_f32_16x16x32_bf16 v[56:59], v[152:155], v[168:171], v[56:59]
	v_mfma_f32_16x16x32_bf16 v[52:55], v[160:163], v[168:171], v[52:55]
	v_mfma_f32_16x16x32_bf16 v[40:43], v[152:155], v[176:179], v[40:43]
	v_mfma_f32_16x16x32_bf16 v[36:39], v[160:163], v[176:179], v[36:39]
	v_mfma_f32_16x16x32_bf16 v[24:27], v[152:155], v[184:187], v[24:27]
	v_mfma_f32_16x16x32_bf16 v[20:23], v[160:163], v[184:187], v[20:23]
	v_mfma_f32_16x16x32_bf16 v[8:11], v[152:155], v[192:195], v[8:11]
	v_mfma_f32_16x16x32_bf16 v[4:7], v[160:163], v[192:195], v[4:7]
	s_setprio 0
	s_add_i32 s70, s70, 2
	s_add_u32 s82, s82, 0x100
	s_addc_u32 s83, s83, 0
	s_add_u32 s92, s92, 0x100
	s_addc_u32 s93, s93, 0
	s_cmp_gt_u32 s70, 13
	s_barrier
	s_cbranch_scc0 .LBB0_428
	s_and_b64 vcc, exec, s[34:35]
	s_cbranch_vccz .LBB0_431
	s_barrier

; #define PG8_STAGE(bufoff, gbase, voff) do { _Pragma("unroll") for (int _i = 0; _i < 2; ++_i) \
;         __builtin_amdgcn_global_load_lds((const unsigned*)((const char*)(gbase) + (voff)[_i]), (PG8_LAS unsigned*)(lds + (bufoff) + ldsw + _i * 8192), 16, 0, 0); } while (0)
; #define PG8_LDA(dst, b, h) do { _Pragma("unroll") for (int m = 0; m < 4; ++m) _Pragma("unroll") for (int k = 0; k < 2; ++k) dst[m][k] = *(const PG8_LAS bf16x8*)(lds + PG8_SA(b, h) + aoff + m * 2048 + k * 1024); } while (0)
; #define PG8_LDB(dst, b, h) do { _Pragma("unroll") for (int n = 0; n < 2; ++n) _Pragma("unroll") for (int k = 0; k < 2; ++k) dst[n][k] = *(const PG8_LAS bf16x8*)(lds + PG8_SB(b, h) + boff + n * 2048 + k * 1024); } while (0)
; #define PG8_MMA(ai, bj, At, Bt) do { __builtin_amdgcn_s_setprio(1); _Pragma("unroll") for (int m = 0; m < 4; ++m) _Pragma("unroll") for (int n = 0; n < 2; ++n) _Pragma("unroll") for (int k = 0; k < 2; ++k) \
;         acc[ai][bj][m][n] = __builtin_amdgcn_mfma_f32_16x16x32_bf16(Bt[n][k], At[m][k], acc[ai][bj][m][n], 0, 0, 0); __builtin_amdgcn_s_setprio(0); } while (0)
; #define PG8_WAIT_V(n) asm volatile("s_waitcnt vmcnt(" #n ")" ::: "memory")
; #define PG8_WAIT_L(n) asm volatile("s_waitcnt lgkmcnt(" #n ")" ::: "memory")
; #define PG8_BAR __builtin_amdgcn_s_barrier()
; #define PG8_SCHED __builtin_amdgcn_sched_barrier(0)
; template <class Epi, class Sched, bool ALIGN_EPI = false, bool SP2 = false>
; __device__ __forceinline__ void gemm_phase(PG8_LAS unsigned char* lds, const Gemm g, const Sched& S, const Epi& E) {
;     ...
;             PG8_LDB(B0, 0, 0); PG8_LDB(B1, 0, 1); PG8_SCHED; PG8_LDA(At, 0, 0); PG8_STAGE(PG8_SA(1, 1), a1 + hstep, voffA);
;             PG8_WAIT_V(8); PG8_WAIT_L(0); PG8_BAR; PG8_MMA(0, 0, At, B0); PG8_MMA(0, 1, At, B1); PG8_BAR; PG8_SCHED;
;             PG8_LDA(At, 0, 1); PG8_STAGE(PG8_SB(0, 0), b2, voffB); PG8_STAGE(PG8_SB(0, 1), b2 + hstep, voffB); PG8_STAGE(PG8_SA(0, 0), a2, voffA);
;             PG8_WAIT_V(8); PG8_WAIT_L(0); PG8_BAR; PG8_MMA(1, 0, At, B0); PG8_MMA(1, 1, At, B1); PG8_BAR; PG8_SCHED;
.LBB0_553:
	s_add_u32 s42, s36, 0xfffc0080
	s_addc_u32 s43, s37, -1
	s_add_i32 s58, 0, 0x10000
	s_cmp_eq_u32 s69, 12
	s_cselect_b32 s55, s27, s43
	s_cselect_b32 s54, s65, s42
	v_add_u32_e32 v149, s58, v146
	s_cselect_b32 s43, s25, s68
	s_cselect_b32 s42, s66, s67
	s_add_i32 s59, 0, 0x14000
	ds_read_b128 v[142:145], v149
	ds_read_b128 v[150:153], v149 offset:1024
	ds_read_b128 v[154:157], v149 offset:2048
	ds_read_b128 v[158:161], v149 offset:3072
	v_add_u32_e32 v149, s59, v146
	ds_read_b128 v[162:165], v149
	ds_read_b128 v[166:169], v149 offset:1024
	ds_read_b128 v[170:173], v149 offset:2048
	ds_read_b128 v[174:177], v149 offset:3072
	v_lshl_add_u64 v[206:207], s[36:37], 0, v[140:141]
	s_add_i32 m0, s11, 0xc000
	ds_read_b128 v[178:181], v148
	ds_read_b128 v[182:185], v148 offset:1024
	ds_read_b128 v[186:189], v148 offset:2048
	ds_read_b128 v[190:193], v148 offset:3072
	ds_read_b128 v[194:197], v148 offset:4096
	ds_read_b128 v[198:201], v148 offset:5120
	ds_read_b128 v[202:205], v148 offset:6144
	ds_read_b128 v[214:217], v148 offset:7168
	global_load_lds_dwordx4 v[206:207], off
	v_lshl_add_u64 v[206:207], s[36:37], 0, v[138:139]
	s_add_i32 m0, s11, 0xe000
	s_nop 0
	global_load_lds_dwordx4 v[206:207], off
	s_waitcnt vmcnt(8)
	s_waitcnt lgkmcnt(0)
	s_barrier
	s_setprio 1
	s_waitcnt lgkmcnt(0)
	v_mfma_f32_16x16x32_bf16 v[128:131], v[142:145], v[178:181], v[128:131]
	v_mfma_f32_16x16x32_bf16 v[124:127], v[154:157], v[178:181], v[124:127]
	v_mfma_f32_16x16x32_bf16 v[120:123], v[142:145], v[186:189], v[120:123]
	v_mfma_f32_16x16x32_bf16 v[112:115], v[154:157], v[186:189], v[112:115]
	v_mfma_f32_16x16x32_bf16 v[104:107], v[142:145], v[194:197], v[104:107]
	v_mfma_f32_16x16x32_bf16 v[96:99], v[154:157], v[194:197], v[96:99]
	v_mfma_f32_16x16x32_bf16 v[88:91], v[142:145], v[202:205], v[88:91]
	v_mfma_f32_16x16x32_bf16 v[80:83], v[154:157], v[202:205], v[80:83]
	v_mfma_f32_16x16x32_bf16 v[128:131], v[150:153], v[182:185], v[128:131]
	v_mfma_f32_16x16x32_bf16 v[124:127], v[158:161], v[182:185], v[124:127]
	v_mfma_f32_16x16x32_bf16 v[120:123], v[150:153], v[190:193], v[120:123]
	v_mfma_f32_16x16x32_bf16 v[112:115], v[158:161], v[190:193], v[112:115]
	v_mfma_f32_16x16x32_bf16 v[104:107], v[150:153], v[198:201], v[104:107]
	v_mfma_f32_16x16x32_bf16 v[96:99], v[158:161], v[198:201], v[96:99]
	v_mfma_f32_16x16x32_bf16 v[88:91], v[150:153], v[214:217], v[88:91]
	v_mfma_f32_16x16x32_bf16 v[80:83], v[158:161], v[214:217], v[80:83]
	s_setprio 0
	s_setprio 1
	v_mfma_f32_16x16x32_bf16 v[116:119], v[162:165], v[178:181], v[116:119]
	v_mfma_f32_16x16x32_bf16 v[108:111], v[170:173], v[178:181], v[108:111]
	v_mfma_f32_16x16x32_bf16 v[100:103], v[162:165], v[186:189], v[100:103]
	v_mfma_f32_16x16x32_bf16 v[92:95], v[170:173], v[186:189], v[92:95]
	v_mfma_f32_16x16x32_bf16 v[84:87], v[162:165], v[194:197], v[84:87]
	v_mfma_f32_16x16x32_bf16 v[76:79], v[170:173], v[194:197], v[76:79]
	v_mfma_f32_16x16x32_bf16 v[72:75], v[162:165], v[202:205], v[72:75]
	v_mfma_f32_16x16x32_bf16 v[68:71], v[170:173], v[202:205], v[68:71]
	v_mfma_f32_16x16x32_bf16 v[116:119], v[166:169], v[182:185], v[116:119]
	v_mfma_f32_16x16x32_bf16 v[108:111], v[174:177], v[182:185], v[108:111]
	v_mfma_f32_16x16x32_bf16 v[100:103], v[166:169], v[190:193], v[100:103]
	v_mfma_f32_16x16x32_bf16 v[92:95], v[174:177], v[190:193], v[92:95]
	v_mfma_f32_16x16x32_bf16 v[84:87], v[166:169], v[198:201], v[84:87]
	v_mfma_f32_16x16x32_bf16 v[76:79], v[174:177], v[198:201], v[76:79]
	v_mfma_f32_16x16x32_bf16 v[72:75], v[166:169], v[214:217], v[72:75]
	v_mfma_f32_16x16x32_bf16 v[68:71], v[174:177], v[214:217], v[68:71]
	s_setprio 0
	s_barrier
	s_add_i32 s58, s58, s8
	v_lshl_add_u64 v[206:207], s[42:43], 0, v[132:133]
	s_mov_b32 m0, s58
	ds_read_b128 v[178:181], v148 offset:16384
	ds_read_b128 v[182:185], v148 offset:17408
	ds_read_b128 v[186:189], v148 offset:18432
	ds_read_b128 v[190:193], v148 offset:19456
	ds_read_b128 v[194:197], v148 offset:20480
	ds_read_b128 v[198:201], v148 offset:21504
	ds_read_b128 v[202:205], v148 offset:22528
	ds_read_b128 v[214:217], v148 offset:23552
	global_load_lds_dwordx4 v[206:207], off
	s_add_i32 m0, s58, 0x2000
	s_add_u32 s70, s42, 0x40000
	v_lshl_add_u64 v[218:219], s[42:43], 0, v[136:137]
	s_addc_u32 s71, s43, 0
	s_add_i32 s58, s59, s8
	global_load_lds_dwordx4 v[218:219], off
	v_lshl_add_u64 v[220:221], s[70:71], 0, v[132:133]
	s_mov_b32 m0, s58
	v_lshl_add_u64 v[222:223], s[54:55], 0, v[134:135]
	global_load_lds_dwordx4 v[220:221], off
	v_lshl_add_u64 v[220:221], s[70:71], 0, v[136:137]
	s_add_i32 m0, s58, 0x2000
	s_nop 0
	global_load_lds_dwordx4 v[220:221], off
	v_lshl_add_u64 v[220:221], s[54:55], 0, v[0:1]
	s_mov_b32 m0, s11
	s_nop 0
	global_load_lds_dwordx4 v[220:221], off
	s_mov_b32 m0, s13
	s_nop 0
	global_load_lds_dwordx4 v[222:223], off
	s_waitcnt vmcnt(8)
	s_waitcnt lgkmcnt(0)
	s_barrier
; #define PG8_STAGE(bufoff, gbase, voff) do { _Pragma("unroll") for (int _i = 0; _i < 2; ++_i) \
;         __builtin_amdgcn_global_load_lds((const unsigned*)((const char*)(gbase) + (voff)[_i]), (PG8_LAS unsigned*)(lds + (bufoff) + ldsw + _i * 8192), 16, 0, 0); } while (0)
; #define PG8_LDA(dst, b, h) do { _Pragma("unroll") for (int m = 0; m < 4; ++m) _Pragma("unroll") for (int k = 0; k < 2; ++k) dst[m][k] = *(const PG8_LAS bf16x8*)(lds + PG8_SA(b, h) + aoff + m * 2048 + k * 1024); } while (0)
; #define PG8_LDB(dst, b, h) do { _Pragma("unroll") for (int n = 0; n < 2; ++n) _Pragma("unroll") for (int k = 0; k < 2; ++k) dst[n][k] = *(const PG8_LAS bf16x8*)(lds + PG8_SB(b, h) + boff + n * 2048 + k * 1024); } while (0)
; #define PG8_MMA(ai, bj, At, Bt) do { __builtin_amdgcn_s_setprio(1); _Pragma("unroll") for (int m = 0; m < 4; ++m) _Pragma("unroll") for (int n = 0; n < 2; ++n) _Pragma("unroll") for (int k = 0; k < 2; ++k) \
;         acc[ai][bj][m][n] = __builtin_amdgcn_mfma_f32_16x16x32_bf16(Bt[n][k], At[m][k], acc[ai][bj][m][n], 0, 0, 0); __builtin_amdgcn_s_setprio(0); } while (0)
; #define PG8_WAIT_V(n) asm volatile("s_waitcnt vmcnt(" #n ")" ::: "memory")
; #define PG8_WAIT_L(n) asm volatile("s_waitcnt lgkmcnt(" #n ")" ::: "memory")
; #define PG8_BAR __builtin_amdgcn_s_barrier()
; #define PG8_SCHED __builtin_amdgcn_sched_barrier(0)
; template <class Epi, class Sched, bool ALIGN_EPI = false, bool SP2 = false>
; __device__ __forceinline__ void gemm_phase(PG8_LAS unsigned char* lds, const Gemm g, const Sched& S, const Epi& E) {
;     ...
;             PG8_WAIT_V(8); PG8_WAIT_L(0); PG8_BAR; PG8_MMA(1, 0, At, B0); PG8_MMA(1, 1, At, B1); PG8_BAR; PG8_SCHED;
;             PG8_LDB(B0, 1, 0); PG8_LDB(B1, 1, 1); PG8_SCHED; PG8_LDA(At, 1, 0); PG8_STAGE(PG8_SA(0, 1), a2 + hstep, voffA);
;             PG8_WAIT_V(8); PG8_WAIT_L(0); PG8_BAR; PG8_MMA(0, 0, At, B0); PG8_MMA(0, 1, At, B1); PG8_BAR; PG8_SCHED;
	s_setprio 1
	s_waitcnt lgkmcnt(0)
	v_mfma_f32_16x16x32_bf16 v[64:67], v[142:145], v[178:181], v[64:67]
	v_mfma_f32_16x16x32_bf16 v[60:63], v[154:157], v[178:181], v[60:63]
	v_mfma_f32_16x16x32_bf16 v[56:59], v[142:145], v[186:189], v[56:59]
	v_mfma_f32_16x16x32_bf16 v[48:51], v[154:157], v[186:189], v[48:51]
	v_mfma_f32_16x16x32_bf16 v[40:43], v[142:145], v[194:197], v[40:43]
	v_mfma_f32_16x16x32_bf16 v[32:35], v[154:157], v[194:197], v[32:35]
	v_mfma_f32_16x16x32_bf16 v[24:27], v[142:145], v[202:205], v[24:27]
	v_mfma_f32_16x16x32_bf16 v[16:19], v[154:157], v[202:205], v[16:19]
	v_mfma_f32_16x16x32_bf16 v[64:67], v[150:153], v[182:185], v[64:67]
	v_mfma_f32_16x16x32_bf16 v[60:63], v[158:161], v[182:185], v[60:63]
	v_mfma_f32_16x16x32_bf16 v[56:59], v[150:153], v[190:193], v[56:59]
	v_mfma_f32_16x16x32_bf16 v[48:51], v[158:161], v[190:193], v[48:51]
	v_mfma_f32_16x16x32_bf16 v[40:43], v[150:153], v[198:201], v[40:43]
	v_mfma_f32_16x16x32_bf16 v[32:35], v[158:161], v[198:201], v[32:35]
	v_mfma_f32_16x16x32_bf16 v[24:27], v[150:153], v[214:217], v[24:27]
	v_mfma_f32_16x16x32_bf16 v[16:19], v[158:161], v[214:217], v[16:19]
	s_setprio 0
	s_setprio 1
	v_mfma_f32_16x16x32_bf16 v[52:55], v[162:165], v[178:181], v[52:55]
	v_mfma_f32_16x16x32_bf16 v[44:47], v[170:173], v[178:181], v[44:47]
	v_mfma_f32_16x16x32_bf16 v[36:39], v[162:165], v[186:189], v[36:39]
	v_mfma_f32_16x16x32_bf16 v[28:31], v[170:173], v[186:189], v[28:31]
	v_mfma_f32_16x16x32_bf16 v[20:23], v[162:165], v[194:197], v[20:23]
	v_mfma_f32_16x16x32_bf16 v[12:15], v[170:173], v[194:197], v[12:15]
	v_mfma_f32_16x16x32_bf16 v[8:11], v[162:165], v[202:205], v[8:11]
	v_mfma_f32_16x16x32_bf16 v[4:7], v[170:173], v[202:205], v[4:7]
	v_mfma_f32_16x16x32_bf16 v[52:55], v[166:169], v[182:185], v[52:55]
	v_mfma_f32_16x16x32_bf16 v[44:47], v[174:177], v[182:185], v[44:47]
	v_mfma_f32_16x16x32_bf16 v[36:39], v[166:169], v[190:193], v[36:39]
	v_mfma_f32_16x16x32_bf16 v[28:31], v[174:177], v[190:193], v[28:31]
	v_mfma_f32_16x16x32_bf16 v[20:23], v[166:169], v[198:201], v[20:23]
	v_mfma_f32_16x16x32_bf16 v[12:15], v[174:177], v[198:201], v[12:15]
	v_mfma_f32_16x16x32_bf16 v[8:11], v[166:169], v[214:217], v[8:11]
	v_mfma_f32_16x16x32_bf16 v[4:7], v[174:177], v[214:217], v[4:7]
	s_setprio 0
	s_barrier
	s_add_i32 s58, 0, 0x18000
	v_add_u32_e32 v149, s58, v146
	s_add_i32 s59, 0, 0x1c000
	ds_read_b128 v[142:145], v149
	ds_read_b128 v[150:153], v149 offset:1024
	ds_read_b128 v[154:157], v149 offset:2048
	ds_read_b128 v[158:161], v149 offset:3072
	v_add_u32_e32 v149, s59, v146
	ds_read_b128 v[162:165], v149
	ds_read_b128 v[166:169], v149 offset:1024
	ds_read_b128 v[170:173], v149 offset:2048
	ds_read_b128 v[174:177], v149 offset:3072
	s_add_u32 s54, s54, 0x40000
	s_addc_u32 s55, s55, 0
	s_mov_b32 m0, s35
	v_lshl_add_u64 v[224:225], s[54:55], 0, v[0:1]
	ds_read_b128 v[178:181], v148 offset:32768
	ds_read_b128 v[182:185], v148 offset:33792
	ds_read_b128 v[186:189], v148 offset:34816
	ds_read_b128 v[190:193], v148 offset:35840
	ds_read_b128 v[194:197], v148 offset:36864
	ds_read_b128 v[198:201], v148 offset:37888
	ds_read_b128 v[202:205], v148 offset:38912
	ds_read_b128 v[214:217], v148 offset:39936
	global_load_lds_dwordx4 v[224:225], off
	v_lshl_add_u64 v[224:225], s[54:55], 0, v[134:135]
	s_mov_b32 m0, s38
	s_nop 0
	global_load_lds_dwordx4 v[224:225], off
	s_waitcnt vmcnt(8)
	s_waitcnt lgkmcnt(0)
	s_barrier
	s_setprio 1
	s_waitcnt lgkmcnt(0)
	v_mfma_f32_16x16x32_bf16 v[128:131], v[142:145], v[178:181], v[128:131]
	v_mfma_f32_16x16x32_bf16 v[124:127], v[154:157], v[178:181], v[124:127]
	v_mfma_f32_16x16x32_bf16 v[120:123], v[142:145], v[186:189], v[120:123]
	v_mfma_f32_16x16x32_bf16 v[112:115], v[154:157], v[186:189], v[112:115]
	v_mfma_f32_16x16x32_bf16 v[104:107], v[142:145], v[194:197], v[104:107]
	v_mfma_f32_16x16x32_bf16 v[96:99], v[154:157], v[194:197], v[96:99]
	v_mfma_f32_16x16x32_bf16 v[88:91], v[142:145], v[202:205], v[88:91]
	v_mfma_f32_16x16x32_bf16 v[80:83], v[154:157], v[202:205], v[80:83]
	v_mfma_f32_16x16x32_bf16 v[128:131], v[150:153], v[182:185], v[128:131]
	v_mfma_f32_16x16x32_bf16 v[124:127], v[158:161], v[182:185], v[124:127]
	v_mfma_f32_16x16x32_bf16 v[120:123], v[150:153], v[190:193], v[120:123]
	v_mfma_f32_16x16x32_bf16 v[112:115], v[158:161], v[190:193], v[112:115]
	v_mfma_f32_16x16x32_bf16 v[104:107], v[150:153], v[198:201], v[104:107]
	v_mfma_f32_16x16x32_bf16 v[96:99], v[158:161], v[198:201], v[96:99]
	v_mfma_f32_16x16x32_bf16 v[88:91], v[150:153], v[214:217], v[88:91]
	v_mfma_f32_16x16x32_bf16 v[80:83], v[158:161], v[214:217], v[80:83]
	s_setprio 0
	s_setprio 1
	v_mfma_f32_16x16x32_bf16 v[116:119], v[162:165], v[178:181], v[116:119]
	v_mfma_f32_16x16x32_bf16 v[108:111], v[170:173], v[178:181], v[108:111]
	v_mfma_f32_16x16x32_bf16 v[100:103], v[162:165], v[186:189], v[100:103]
	v_mfma_f32_16x16x32_bf16 v[92:95], v[170:173], v[186:189], v[92:95]
	v_mfma_f32_16x16x32_bf16 v[84:87], v[162:165], v[194:197], v[84:87]
	v_mfma_f32_16x16x32_bf16 v[76:79], v[170:173], v[194:197], v[76:79]
	v_mfma_f32_16x16x32_bf16 v[72:75], v[162:165], v[202:205], v[72:75]
	v_mfma_f32_16x16x32_bf16 v[68:71], v[170:173], v[202:205], v[68:71]
	v_mfma_f32_16x16x32_bf16 v[116:119], v[166:169], v[182:185], v[116:119]
	v_mfma_f32_16x16x32_bf16 v[108:111], v[174:177], v[182:185], v[108:111]
	v_mfma_f32_16x16x32_bf16 v[100:103], v[166:169], v[190:193], v[100:103]
	v_mfma_f32_16x16x32_bf16 v[92:95], v[174:177], v[190:193], v[92:95]
	v_mfma_f32_16x16x32_bf16 v[84:87], v[166:169], v[198:201], v[84:87]
	v_mfma_f32_16x16x32_bf16 v[76:79], v[174:177], v[198:201], v[76:79]
	v_mfma_f32_16x16x32_bf16 v[72:75], v[166:169], v[214:217], v[72:75]
	v_mfma_f32_16x16x32_bf16 v[68:71], v[174:177], v[214:217], v[68:71]
	s_setprio 0
	s_barrier
; #define PG8_STAGE(bufoff, gbase, voff) do { _Pragma("unroll") for (int _i = 0; _i < 2; ++_i) \
;         __builtin_amdgcn_global_load_lds((const unsigned*)((const char*)(gbase) + (voff)[_i]), (PG8_LAS unsigned*)(lds + (bufoff) + ldsw + _i * 8192), 16, 0, 0); } while (0)
; #define PG8_LDA(dst, b, h) do { _Pragma("unroll") for (int m = 0; m < 4; ++m) _Pragma("unroll") for (int k = 0; k < 2; ++k) dst[m][k] = *(const PG8_LAS bf16x8*)(lds + PG8_SA(b, h) + aoff + m * 2048 + k * 1024); } while (0)
; #define PG8_MMA(ai, bj, At, Bt) do { __builtin_amdgcn_s_setprio(1); _Pragma("unroll") for (int m = 0; m < 4; ++m) _Pragma("unroll") for (int n = 0; n < 2; ++n) _Pragma("unroll") for (int k = 0; k < 2; ++k) \
;         acc[ai][bj][m][n] = __builtin_amdgcn_mfma_f32_16x16x32_bf16(Bt[n][k], At[m][k], acc[ai][bj][m][n], 0, 0, 0); __builtin_amdgcn_s_setprio(0); } while (0)
; #define PG8_WAIT_V(n) asm volatile("s_waitcnt vmcnt(" #n ")" ::: "memory")
; #define PG8_WAIT_L(n) asm volatile("s_waitcnt lgkmcnt(" #n ")" ::: "memory")
; #define PG8_BAR __builtin_amdgcn_s_barrier()
; #define PG8_SCHED __builtin_amdgcn_sched_barrier(0)
; template <class Epi, class Sched, bool ALIGN_EPI = false, bool SP2 = false>
; __device__ __forceinline__ void gemm_phase(PG8_LAS unsigned char* lds, const Gemm g, const Sched& S, const Epi& E) {
;     ...
;             PG8_LDA(At, 1, 1); PG8_STAGE(PG8_SB(1, 0), b3, voffB); PG8_STAGE(PG8_SB(1, 1), b3 + hstep, voffB); PG8_STAGE(PG8_SA(1, 0), a3, voffA);
;             PG8_WAIT_V(8); PG8_WAIT_L(0); PG8_BAR; PG8_MMA(1, 0, At, B0); PG8_MMA(1, 1, At, B1); PG8_BAR; PG8_SCHED;
	s_add_i32 s54, s58, s8
	v_lshl_add_u64 v[206:207], v[206:207], 0, s[52:53]
	s_mov_b32 m0, s54
	ds_read_b128 v[178:181], v148 offset:49152
	ds_read_b128 v[182:185], v148 offset:50176
	ds_read_b128 v[186:189], v148 offset:51200
	ds_read_b128 v[190:193], v148 offset:52224
	ds_read_b128 v[194:197], v148 offset:53248
	ds_read_b128 v[198:201], v148 offset:54272
	ds_read_b128 v[202:205], v148 offset:55296
	ds_read_b128 v[214:217], v148 offset:56320
	global_load_lds_dwordx4 v[206:207], off
	s_add_i32 m0, s54, 0x2000
	s_add_u32 s42, s42, 0x40080
	v_lshl_add_u64 v[206:207], v[218:219], 0, s[52:53]
	s_addc_u32 s43, s43, 0
	s_add_i32 s54, s59, s8
	global_load_lds_dwordx4 v[206:207], off
	v_lshl_add_u64 v[206:207], s[42:43], 0, v[132:133]
	s_mov_b32 m0, s54
	s_nop 0
	global_load_lds_dwordx4 v[206:207], off
	v_lshl_add_u64 v[206:207], s[42:43], 0, v[136:137]
	s_add_i32 m0, s54, 0x2000
	s_nop 0
	global_load_lds_dwordx4 v[206:207], off
	v_lshl_add_u64 v[206:207], v[220:221], 0, s[52:53]
	s_mov_b32 m0, s45
	s_nop 0
	global_load_lds_dwordx4 v[206:207], off
	v_lshl_add_u64 v[206:207], v[222:223], 0, s[52:53]
	s_mov_b32 m0, s46
	s_nop 0
	global_load_lds_dwordx4 v[206:207], off
	s_waitcnt vmcnt(8)
	s_waitcnt lgkmcnt(0)
	s_barrier
	s_setprio 1
	s_waitcnt lgkmcnt(0)
	v_mfma_f32_16x16x32_bf16 v[64:67], v[142:145], v[178:181], v[64:67]
	v_mfma_f32_16x16x32_bf16 v[60:63], v[154:157], v[178:181], v[60:63]
	v_mfma_f32_16x16x32_bf16 v[56:59], v[142:145], v[186:189], v[56:59]
	v_mfma_f32_16x16x32_bf16 v[48:51], v[154:157], v[186:189], v[48:51]
	v_mfma_f32_16x16x32_bf16 v[40:43], v[142:145], v[194:197], v[40:43]
	v_mfma_f32_16x16x32_bf16 v[32:35], v[154:157], v[194:197], v[32:35]
	v_mfma_f32_16x16x32_bf16 v[24:27], v[142:145], v[202:205], v[24:27]
	v_mfma_f32_16x16x32_bf16 v[16:19], v[154:157], v[202:205], v[16:19]
	v_mfma_f32_16x16x32_bf16 v[64:67], v[150:153], v[182:185], v[64:67]
	v_mfma_f32_16x16x32_bf16 v[60:63], v[158:161], v[182:185], v[60:63]
	v_mfma_f32_16x16x32_bf16 v[56:59], v[150:153], v[190:193], v[56:59]
	v_mfma_f32_16x16x32_bf16 v[48:51], v[158:161], v[190:193], v[48:51]
	v_mfma_f32_16x16x32_bf16 v[40:43], v[150:153], v[198:201], v[40:43]
	v_mfma_f32_16x16x32_bf16 v[32:35], v[158:161], v[198:201], v[32:35]
	v_mfma_f32_16x16x32_bf16 v[24:27], v[150:153], v[214:217], v[24:27]
	v_mfma_f32_16x16x32_bf16 v[16:19], v[158:161], v[214:217], v[16:19]
	s_setprio 0
	s_setprio 1
	v_mfma_f32_16x16x32_bf16 v[52:55], v[162:165], v[178:181], v[52:55]
	v_mfma_f32_16x16x32_bf16 v[44:47], v[170:173], v[178:181], v[44:47]
	v_mfma_f32_16x16x32_bf16 v[36:39], v[162:165], v[186:189], v[36:39]
	v_mfma_f32_16x16x32_bf16 v[28:31], v[170:173], v[186:189], v[28:31]
	v_mfma_f32_16x16x32_bf16 v[20:23], v[162:165], v[194:197], v[20:23]
	v_mfma_f32_16x16x32_bf16 v[12:15], v[170:173], v[194:197], v[12:15]
	v_mfma_f32_16x16x32_bf16 v[8:11], v[162:165], v[202:205], v[8:11]
	v_mfma_f32_16x16x32_bf16 v[4:7], v[170:173], v[202:205], v[4:7]
	v_mfma_f32_16x16x32_bf16 v[52:55], v[166:169], v[182:185], v[52:55]
	v_mfma_f32_16x16x32_bf16 v[44:47], v[174:177], v[182:185], v[44:47]
	v_mfma_f32_16x16x32_bf16 v[36:39], v[166:169], v[190:193], v[36:39]
	v_mfma_f32_16x16x32_bf16 v[28:31], v[174:177], v[190:193], v[28:31]
	v_mfma_f32_16x16x32_bf16 v[20:23], v[166:169], v[198:201], v[20:23]
	v_mfma_f32_16x16x32_bf16 v[12:15], v[174:177], v[198:201], v[12:15]
	v_mfma_f32_16x16x32_bf16 v[8:11], v[166:169], v[214:217], v[8:11]
	v_mfma_f32_16x16x32_bf16 v[4:7], v[174:177], v[214:217], v[4:7]
	s_setprio 0
	s_add_i32 s69, s69, 2
	s_add_u32 s67, s67, 0x100
	s_addc_u32 s68, s68, 0
	s_add_u32 s36, s36, 0x100
	s_addc_u32 s37, s37, 0
	s_cmp_gt_u32 s69, 13
	s_barrier
	s_cbranch_scc0 .LBB0_553
	s_and_b64 vcc, exec, s[22:23]
	s_cbranch_vccz .LBB0_556
	s_barrier
